# scan E roles: bf16 operands fetched with ds_read_u16_d16_hi so the 24 widening shifts per step are gone
# speedup vs baseline: 1.0120x; 1.0000x over previous
.LBB0_718:
	s_mov_b64 s[4:5], -1
	s_mov_b64 s[10:11], 0
	s_cmp_lt_i32 s70, 5
	s_mov_b64 s[46:47], 0
	s_barrier
	s_cbranch_scc1 .LBB0_770
	s_cmp_gt_i32 s70, 5
	s_cbranch_scc0 .LBB0_754
	s_cmp_gt_i32 s70, 6
	s_cbranch_scc0 .LBB0_738
	s_cmp_eq_u32 s70, 7
	s_mov_b64 s[46:47], -1
	s_cbranch_scc0 .LBB0_737
	v_lshlrev_b32_e32 v5, 1, v148
	s_add_i32 s4, 0, 0x19c00
	v_add_u32_e32 v2, s4, v5
	ds_read_u16 v29, v2 offset:6656
	v_mov_b32_e32 v12, 0
	v_mov_b32_e32 v13, 0
	v_mov_b32_e32 v14, 0
	v_mov_b32_e32 v15, 0
	v_mov_b32_e32 v24, 0
	v_mov_b32_e32 v25, 0
	v_mov_b32_e32 v26, 0
	v_mov_b32_e32 v27, 0
	v_mov_b32_e32 v42, 0
	v_mov_b32_e32 v43, 0
	v_mov_b32_e32 v44, 0
	v_mov_b32_e32 v45, 0
	v_mov_b32_e32 v46, 0
	v_mov_b32_e32 v47, 0
	v_mov_b32_e32 v48, 0
	v_mov_b32_e32 v49, 0
	v_mov_b32_e32 v50, 0
	v_mov_b32_e32 v51, 0
	v_mov_b32_e32 v52, 0
	v_mov_b32_e32 v57, 0
	v_mov_b32_e32 v58, 0
	v_mov_b32_e32 v59, 0
	v_mov_b32_e32 v60, 0
	v_mov_b32_e32 v61, 0
	v_mov_b32_e32 v62, 0
	v_mov_b32_e32 v63, 0
	v_mov_b32_e32 v64, 0
	v_mov_b32_e32 v65, 0
	v_mov_b32_e32 v66, 0
	v_mov_b32_e32 v67, 0
	v_mov_b32_e32 v68, 0
	v_mov_b32_e32 v69, 0
	v_mov_b32_e32 v70, 0
	v_mov_b32_e32 v71, 0
	v_mov_b32_e32 v72, 0
	v_mov_b32_e32 v74, 0
	v_mov_b32_e32 v76, 0
	v_mov_b32_e32 v78, 0
	v_mov_b32_e32 v80, 0
	v_mov_b32_e32 v81, 0
	v_mov_b32_e32 v82, 0
	v_mov_b32_e32 v83, 0
	v_mov_b32_e32 v84, 0
	v_mov_b32_e32 v85, 0
	v_mov_b32_e32 v86, 0
	v_mov_b32_e32 v87, 0
	v_mov_b32_e32 v88, 0
	ds_read_u16_d16_hi v42, v2 offset:6784
	ds_read_u16_d16_hi v43, v2 offset:6912
	ds_read_u16_d16_hi v44, v2 offset:7040
	ds_read_u16_d16_hi v45, v2 offset:7168
	ds_read_u16_d16_hi v46, v2 offset:7296
	ds_read_u16_d16_hi v47, v2 offset:7424
	ds_read_u16_d16_hi v48, v2 offset:7552
	v_add_u32_e32 v3, s4, v148
	ds_read_u16_d16_hi v49, v2 offset:7680
	ds_read_u16_d16_hi v50, v2 offset:7808
	ds_read_u16_d16_hi v51, v2 offset:7936
	ds_read_u16_d16_hi v52, v2 offset:8064
	ds_read_u8 v1, v3 offset:9024
	ds_read_u8 v9, v3 offset:9152
	ds_read_u8 v0, v3 offset:9088
	ds_read_u8 v8, v3 offset:8960
	ds_read_u16_d16_hi v59, v2 offset:1536
	ds_read_u16_d16_hi v12, v2 offset:3584
	ds_read_u16_d16_hi v62, v2 offset:1664
	ds_read_u16_d16_hi v13, v2 offset:3712
	ds_read_u16_d16_hi v65, v2 offset:1792
	ds_read_u16_d16_hi v14, v2 offset:3840
	ds_read_u16_d16_hi v15, v2 offset:3968
	ds_read_u16_d16_hi v68, v2 offset:1920
	ds_read_u16_d16_hi v69, v2 offset:6144
	ds_read_u16_d16_hi v70, v2 offset:6272
	ds_read_u16_d16_hi v71, v2 offset:6400
	ds_read_u16_d16_hi v72, v2 offset:6528
	ds_read_u16 v73, v2 offset:5632
	ds_read_u16 v75, v2 offset:5760
	ds_read_u16 v77, v2 offset:5888
	ds_read_u16 v79, v2 offset:6016
	s_add_i32 s4, 0, 0x1c4c0
	v_mov_b32_e32 v7, s4
	s_add_i32 s4, 0, 0x1c4d0
	v_mov_b32_e32 v3, s4
	s_add_i32 s4, 0, 0x1c4e0
	v_mov_b32_e32 v10, s4
	s_add_i32 s4, 0, 0x1c4f0
	v_mov_b32_e32 v11, s4
	ds_read_b32 v2, v7
	ds_read_b32 v3, v3
	ds_read_b32 v10, v10
	ds_read_b32 v11, v11
	v_and_b32_e32 v7, 1, v128
	v_lshrrev_b32_e32 v16, 1, v128
	v_cmp_eq_u32_e64 s[6:7], 0, v7
	v_and_b32_e32 v7, 50, v128
	v_and_b32_e32 v5, 8, v5
	v_and_b32_e32 v16, 4, v16
	v_or3_b32 v53, v16, v7, v5
	v_and_b32_e32 v5, 32, v128
	v_and_b32_e32 v7, 31, v128
	s_mov_b32 s13, 0
	v_mul_u32_u24_e32 v54, 0x50, v148
	v_mul_u32_u24_e32 v55, 48, v5
	v_mul_u32_u24_e32 v56, 48, v7
	v_mov_b32_e32 v5, v4
	v_mov_b32_e32 v7, v6
	s_mov_b32 s12, 0x3b808081
	s_waitcnt lgkmcnt(0)
	s_branch .LBB0_725

.LBB0_725:
	s_add_i32 s16, s13, 1
	s_cmpk_lt_u32 s13, 0x200
	s_cselect_b64 s[14:15], -1, 0
	s_cmpk_gt_u32 s13, 0x1ff
	s_cbranch_scc1 .LBB0_727
	s_mul_i32 s4, s16, 0xcccd
	s_lshr_b32 s4, s4, 18
	s_mul_i32 s4, s4, 5
	s_sub_i32 s4, s16, s4
	s_and_b32 s4, s4, 0xffff
	s_mulk_i32 s4, 0x2900
	s_add_i32 s4, s4, 0
	s_add_i32 s4, s4, 0x19c00
	v_mov_b32_e32 v16, s4
	v_lshl_add_u32 v28, v148, 1, s4
	v_add_u32_e32 v20, s4, v148
	v_add_u32_e32 v18, 0x2800, v16
	ds_read_u16_d16_hi v57, v28 offset:6656
	ds_read_u16_d16_hi v58, v28 offset:6784
	ds_read_u16_d16_hi v60, v28 offset:6912
	ds_read_u16_d16_hi v61, v28 offset:7040
	ds_read_u16_d16_hi v63, v28 offset:7168
	ds_read_u16_d16_hi v64, v28 offset:7296
	ds_read_u16_d16_hi v66, v28 offset:7424
	ds_read_u16_d16_hi v67, v28 offset:7552
	ds_read2_b32 v[16:17], v18 offset0:48 offset1:52
	ds_read2_b32 v[18:19], v18 offset0:56 offset1:60
	ds_read_u16_d16_hi v74, v28 offset:7680
	ds_read_u16_d16_hi v76, v28 offset:7808
	ds_read_u16_d16_hi v78, v28 offset:7936
	ds_read_u16_d16_hi v80, v28 offset:8064
	ds_read_u8 v21, v20 offset:9024
	ds_read_u8 v23, v20 offset:9152
	ds_read_u8 v22, v20 offset:9088
	ds_read_u8 v20, v20 offset:8960
	ds_read_u16_d16_hi v85, v28 offset:1536
	ds_read_u16_d16_hi v24, v28 offset:3584
	ds_read_u16_d16_hi v86, v28 offset:1664
	ds_read_u16_d16_hi v25, v28 offset:3712
	ds_read_u16_d16_hi v87, v28 offset:1792
	ds_read_u16_d16_hi v26, v28 offset:3840
	ds_read_u16_d16_hi v27, v28 offset:3968
	ds_read_u16_d16_hi v88, v28 offset:1920
	ds_read_u16_d16_hi v81, v28 offset:6144
	ds_read_u16_d16_hi v82, v28 offset:6272
	ds_read_u16_d16_hi v83, v28 offset:6400
	ds_read_u16_d16_hi v84, v28 offset:6528
	ds_read_u16 v89, v28 offset:5632
	ds_read_u16 v90, v28 offset:5760
	ds_read_u16 v91, v28 offset:5888
	ds_read_u16 v92, v28 offset:6016
.LBB0_727:
	v_cndmask_b32_e64 v28, 0, 1, s[14:15]
	v_cmp_ne_u32_e64 s[8:9], 1, v28
	s_andn2_b64 vcc, exec, s[14:15]
	s_cbranch_vccnz .LBB0_731
	v_add_f32_e32 v28, 0, v69
	v_add_f32_e32 v28, v28, v70
	v_add_f32_e32 v28, v28, v71
	v_add_f32_e32 v28, v28, v72
	v_lshlrev_b32_e32 v30, 16, v29
	v_add_f32_e32 v28, v28, v30
	v_add_f32_e32 v28, v28, v42
	v_add_f32_e32 v28, v28, v43
	v_add_f32_e32 v28, v28, v44
	v_add_f32_e32 v28, v28, v45
	v_add_f32_e32 v28, v28, v46
	v_add_f32_e32 v28, v28, v47
	v_add_f32_e32 v30, v28, v48
	v_add_f32_e32 v31, v30, v49
	v_add_f32_e32 v40, v31, v50
	v_exp_f32_e32 v101, v31
	v_cvt_f32_u32_e32 v37, v1
	v_cvt_f32_u32_e32 v36, v8
	v_add_f32_e32 v109, v40, v51
	v_add_f32_e32 v28, v109, v52
	v_exp_f32_e32 v28, v28
	v_exp_f32_e32 v41, v30
	v_exp_f32_e32 v111, v40
	v_exp_f32_e32 v120, v109
	v_mul_f32_e32 v93, v101, v59
	v_pk_mul_f32 v[32:33], v[36:37], s[12:13] op_sel_hi:[1,0]
	v_pk_fma_f32 v[36:37], v[36:37], s[12:13], -1.0 op_sel_hi:[1,0,0]
	v_cvt_f32_u32_e32 v117, v9
	v_cvt_f32_u32_e32 v116, v0
	v_pk_mul_f32 v[38:39], v[4:5], v[12:13]
	v_pk_fma_f32 v[36:37], v[6:7], v[36:37], 1.0 op_sel_hi:[1,1,0]
	v_pk_mul_f32 v[38:39], v[38:39], v[2:3]
	v_pk_mul_f32 v[34:35], v[36:37], v[12:13]
	v_rcp_f32_e32 v30, v101
	v_mul_f32_e32 v95, v41, v38
	v_rcp_f32_e32 v31, v111
	v_rcp_f32_e32 v36, v120
	v_mul_f32_e32 v109, v120, v65
	v_rcp_f32_e32 v37, v28
	v_pk_mul_f32 v[32:33], v[32:33], v[38:39]
	v_mul_f32_e32 v101, v101, v39
	v_pk_mul_f32 v[38:39], v[116:117], s[12:13] op_sel_hi:[1,0]
	v_pk_mul_f32 v[112:113], v[4:5], v[14:15]
	v_pk_fma_f32 v[116:117], v[116:117], s[12:13], -1.0 op_sel_hi:[1,0,0]
	v_pk_mul_f32 v[118:119], v[112:113], v[10:11]
	v_pk_fma_f32 v[116:117], v[6:7], v[116:117], 1.0 op_sel_hi:[1,1,0]
	s_and_b32 s4, s13, 2
	v_pk_mul_f32 v[38:39], v[38:39], v[118:119]
	v_pk_mul_f32 v[40:41], v[116:117], v[14:15]
	s_mulk_i32 s4, 0x5f00
	v_mul_f32_e32 v97, v30, v32
	v_mul_f32_e32 v99, v30, v34
	v_mul_f32_e32 v102, v111, v62
	v_mul_f32_e32 v103, v31, v33
	v_mul_f32_e32 v105, v31, v35
	v_mul_f32_e32 v111, v111, v118
	v_mul_f32_e32 v113, v36, v38
	v_mul_f32_e32 v115, v36, v40
	v_mul_f32_e32 v117, v120, v119
	v_mul_f32_e32 v118, v28, v68
	v_mul_f32_e32 v119, v37, v39
	v_mul_f32_e32 v121, v37, v41
	s_add_i32 s14, s4, 0
	v_mov_b32_dpp v94, v93 quad_perm:[1,1,3,3] row_mask:0xf bank_mask:0xf bound_ctrl:1
	v_mov_b32_dpp v96, v95 quad_perm:[1,1,3,3] row_mask:0xf bank_mask:0xf bound_ctrl:1
	v_mov_b32_dpp v98, v97 quad_perm:[1,1,3,3] row_mask:0xf bank_mask:0xf bound_ctrl:1
	v_mov_b32_dpp v100, v99 quad_perm:[1,1,3,3] row_mask:0xf bank_mask:0xf bound_ctrl:1
	v_mov_b32_dpp v104, v101 quad_perm:[1,1,3,3] row_mask:0xf bank_mask:0xf bound_ctrl:1
	v_mov_b32_dpp v106, v102 quad_perm:[1,1,3,3] row_mask:0xf bank_mask:0xf bound_ctrl:1
	v_mov_b32_dpp v107, v103 quad_perm:[1,1,3,3] row_mask:0xf bank_mask:0xf bound_ctrl:1
	v_mov_b32_dpp v108, v105 quad_perm:[1,1,3,3] row_mask:0xf bank_mask:0xf bound_ctrl:1
	v_mov_b32_dpp v110, v109 quad_perm:[1,1,3,3] row_mask:0xf bank_mask:0xf bound_ctrl:1
	v_mov_b32_dpp v112, v111 quad_perm:[1,1,3,3] row_mask:0xf bank_mask:0xf bound_ctrl:1
	v_mov_b32_dpp v114, v113 quad_perm:[1,1,3,3] row_mask:0xf bank_mask:0xf bound_ctrl:1
	v_mov_b32_dpp v116, v115 quad_perm:[1,1,3,3] row_mask:0xf bank_mask:0xf bound_ctrl:1
	v_mov_b32_dpp v120, v117 quad_perm:[1,1,3,3] row_mask:0xf bank_mask:0xf bound_ctrl:1
	v_mov_b32_dpp v122, v118 quad_perm:[1,1,3,3] row_mask:0xf bank_mask:0xf bound_ctrl:1
	v_mov_b32_dpp v123, v119 quad_perm:[1,1,3,3] row_mask:0xf bank_mask:0xf bound_ctrl:1
	v_mov_b32_dpp v124, v121 quad_perm:[1,1,3,3] row_mask:0xf bank_mask:0xf bound_ctrl:1
	s_and_saveexec_b64 s[4:5], s[6:7]
	s_cbranch_execz .LBB0_730
	v_cvt_pk_bf16_f32 v93, v93, v94
	v_cvt_pk_bf16_f32 v94, v95, v96
	v_lshl_add_u32 v95, v53, 1, s14
	v_cvt_pk_bf16_f32 v101, v101, v104
	v_add_u32_e32 v96, 0x400, v95
	v_cvt_pk_bf16_f32 v102, v102, v106
	ds_write2_b32 v96, v94, v101 offset0:176 offset1:212
	v_add_u32_e32 v94, 0xe00, v95
	v_cvt_pk_bf16_f32 v118, v118, v122
	v_cvt_pk_bf16_f32 v117, v117, v120
	v_cvt_pk_bf16_f32 v109, v109, v110
	v_cvt_pk_bf16_f32 v110, v111, v112
	v_cvt_pk_bf16_f32 v105, v105, v108
	v_cvt_pk_bf16_f32 v103, v103, v107
	v_cvt_pk_bf16_f32 v99, v99, v100
	v_cvt_pk_bf16_f32 v97, v97, v98
	ds_write2_b32 v94, v93, v102 offset0:112 offset1:148
	v_add_u32_e32 v93, 0x1800, v95
	v_add_u32_e32 v94, 0x2000, v95
	v_add_u32_e32 v96, 0x600, v95
	v_add_u32_e32 v95, 0x1000, v95
	v_cvt_pk_bf16_f32 v121, v121, v124
	v_cvt_pk_bf16_f32 v119, v119, v123
	v_cvt_pk_bf16_f32 v115, v115, v116
	v_cvt_pk_bf16_f32 v113, v113, v114
	ds_write2_b32 v93, v97, v103 offset0:48 offset1:84
	ds_write2_b32 v94, v99, v105 offset0:112 offset1:148
	ds_write2_b32 v96, v110, v117 offset0:120 offset1:156
	ds_write2_b32 v95, v109, v118 offset0:56 offset1:92
	ds_write2_b32 v93, v113, v119 offset0:120 offset1:156
	ds_write2_b32 v94, v115, v121 offset0:184 offset1:220

.LBB0_731:
	s_waitcnt lgkmcnt(0)
	s_barrier
	s_add_i32 s14, s13, 2
	s_cmpk_gt_u32 s13, 0x1fd
	s_cbranch_scc1 .LBB0_733
	s_mul_i32 s4, s14, 0xcccd
	s_lshr_b32 s4, s4, 18
	s_mul_i32 s4, s4, 5
	s_sub_i32 s4, s14, s4
	s_and_b32 s4, s4, 0xffff
	s_mulk_i32 s4, 0x2900
	s_add_i32 s4, s4, 0
	s_add_i32 s4, s4, 0x19c00
	v_mov_b32_e32 v0, s4
	v_lshl_add_u32 v28, v148, 1, s4
	v_add_u32_e32 v8, s4, v148
	v_add_u32_e32 v0, 0x2800, v0
	ds_read_u16 v29, v28 offset:6656
	ds_read_u16_d16_hi v42, v28 offset:6784
	ds_read_u16_d16_hi v43, v28 offset:6912
	ds_read_u16_d16_hi v44, v28 offset:7040
	ds_read_u16_d16_hi v45, v28 offset:7168
	ds_read_u16_d16_hi v46, v28 offset:7296
	ds_read_u16_d16_hi v47, v28 offset:7424
	ds_read_u16_d16_hi v48, v28 offset:7552
	ds_read2_b32 v[2:3], v0 offset0:48 offset1:52
	ds_read2_b32 v[10:11], v0 offset0:56 offset1:60
	ds_read_u16_d16_hi v49, v28 offset:7680
	ds_read_u16_d16_hi v50, v28 offset:7808
	ds_read_u16_d16_hi v51, v28 offset:7936
	ds_read_u16_d16_hi v52, v28 offset:8064
	ds_read_u8 v1, v8 offset:9024
	ds_read_u8 v9, v8 offset:9152
	ds_read_u8 v0, v8 offset:9088
	ds_read_u8 v8, v8 offset:8960
	ds_read_u16_d16_hi v59, v28 offset:1536
	ds_read_u16_d16_hi v12, v28 offset:3584
	ds_read_u16_d16_hi v62, v28 offset:1664
	ds_read_u16_d16_hi v13, v28 offset:3712
	ds_read_u16_d16_hi v65, v28 offset:1792
	ds_read_u16_d16_hi v14, v28 offset:3840
	ds_read_u16_d16_hi v15, v28 offset:3968
	ds_read_u16_d16_hi v68, v28 offset:1920
	ds_read_u16_d16_hi v69, v28 offset:6144
	ds_read_u16_d16_hi v70, v28 offset:6272
	ds_read_u16_d16_hi v71, v28 offset:6400
	ds_read_u16_d16_hi v72, v28 offset:6528
	ds_read_u16 v73, v28 offset:5632
	ds_read_u16 v75, v28 offset:5760
	ds_read_u16 v77, v28 offset:5888
	ds_read_u16 v79, v28 offset:6016
.LBB0_733:
	s_and_b64 vcc, exec, s[8:9]
	s_cbranch_vccnz .LBB0_724
	v_add_f32_e32 v28, 0, v81
	v_add_f32_e32 v28, v28, v82
	v_add_f32_e32 v28, v28, v83
	v_add_f32_e32 v28, v28, v84
	v_add_f32_e32 v28, v28, v57
	v_add_f32_e32 v28, v28, v58
	v_add_f32_e32 v28, v28, v60
	v_add_f32_e32 v28, v28, v61
	v_add_f32_e32 v28, v28, v63
	v_add_f32_e32 v28, v28, v64
	v_add_f32_e32 v28, v28, v66
	v_add_f32_e32 v30, v28, v67
	v_add_f32_e32 v31, v30, v74
	v_add_f32_e32 v40, v31, v76
	v_exp_f32_e32 v101, v31
	v_cvt_f32_u32_e32 v37, v21
	v_cvt_f32_u32_e32 v36, v20
	v_add_f32_e32 v109, v40, v78
	v_add_f32_e32 v28, v109, v80
	v_exp_f32_e32 v28, v28
	v_exp_f32_e32 v41, v30
	v_exp_f32_e32 v111, v40
	v_exp_f32_e32 v120, v109
	v_mul_f32_e32 v93, v101, v85
	v_pk_mul_f32 v[32:33], v[36:37], s[12:13] op_sel_hi:[1,0]
	v_pk_fma_f32 v[36:37], v[36:37], s[12:13], -1.0 op_sel_hi:[1,0,0]
	v_cvt_f32_u32_e32 v117, v23
	v_cvt_f32_u32_e32 v116, v22
	v_pk_mul_f32 v[38:39], v[4:5], v[24:25]
	v_pk_fma_f32 v[36:37], v[6:7], v[36:37], 1.0 op_sel_hi:[1,1,0]
	v_pk_mul_f32 v[38:39], v[16:17], v[38:39]
	v_pk_mul_f32 v[34:35], v[36:37], v[24:25]
	v_rcp_f32_e32 v30, v101
	v_mul_f32_e32 v95, v38, v41
	v_rcp_f32_e32 v31, v111
	v_rcp_f32_e32 v36, v120
	v_mul_f32_e32 v109, v120, v87
	v_rcp_f32_e32 v37, v28
	v_pk_mul_f32 v[32:33], v[32:33], v[38:39]
	v_mul_f32_e32 v101, v39, v101
	v_pk_mul_f32 v[38:39], v[116:117], s[12:13] op_sel_hi:[1,0]
	v_pk_mul_f32 v[112:113], v[4:5], v[26:27]
	v_pk_fma_f32 v[116:117], v[116:117], s[12:13], -1.0 op_sel_hi:[1,0,0]
	v_pk_mul_f32 v[118:119], v[18:19], v[112:113]
	v_pk_fma_f32 v[116:117], v[6:7], v[116:117], 1.0 op_sel_hi:[1,1,0]
	s_and_b32 s4, s16, 3
	v_pk_mul_f32 v[38:39], v[38:39], v[118:119]
	v_pk_mul_f32 v[40:41], v[116:117], v[26:27]
	s_mulk_i32 s4, 0x5f00
	v_mul_f32_e32 v97, v32, v30
	v_mul_f32_e32 v99, v34, v30
	v_mul_f32_e32 v102, v111, v86
	v_mul_f32_e32 v103, v33, v31
	v_mul_f32_e32 v105, v35, v31
	v_mul_f32_e32 v111, v118, v111
	v_mul_f32_e32 v113, v38, v36
	v_mul_f32_e32 v115, v40, v36
	v_mul_f32_e32 v117, v119, v120
	v_mul_f32_e32 v118, v28, v88
	v_mul_f32_e32 v119, v39, v37
	v_mul_f32_e32 v121, v41, v37
	s_add_i32 s8, s4, 0
	v_mov_b32_dpp v94, v93 quad_perm:[1,1,3,3] row_mask:0xf bank_mask:0xf bound_ctrl:1
	v_mov_b32_dpp v96, v95 quad_perm:[1,1,3,3] row_mask:0xf bank_mask:0xf bound_ctrl:1
	v_mov_b32_dpp v98, v97 quad_perm:[1,1,3,3] row_mask:0xf bank_mask:0xf bound_ctrl:1
	v_mov_b32_dpp v100, v99 quad_perm:[1,1,3,3] row_mask:0xf bank_mask:0xf bound_ctrl:1
	v_mov_b32_dpp v104, v101 quad_perm:[1,1,3,3] row_mask:0xf bank_mask:0xf bound_ctrl:1
	v_mov_b32_dpp v106, v102 quad_perm:[1,1,3,3] row_mask:0xf bank_mask:0xf bound_ctrl:1
	v_mov_b32_dpp v107, v103 quad_perm:[1,1,3,3] row_mask:0xf bank_mask:0xf bound_ctrl:1
	v_mov_b32_dpp v108, v105 quad_perm:[1,1,3,3] row_mask:0xf bank_mask:0xf bound_ctrl:1
	v_mov_b32_dpp v110, v109 quad_perm:[1,1,3,3] row_mask:0xf bank_mask:0xf bound_ctrl:1
	v_mov_b32_dpp v112, v111 quad_perm:[1,1,3,3] row_mask:0xf bank_mask:0xf bound_ctrl:1
	v_mov_b32_dpp v114, v113 quad_perm:[1,1,3,3] row_mask:0xf bank_mask:0xf bound_ctrl:1
	v_mov_b32_dpp v116, v115 quad_perm:[1,1,3,3] row_mask:0xf bank_mask:0xf bound_ctrl:1
	v_mov_b32_dpp v120, v117 quad_perm:[1,1,3,3] row_mask:0xf bank_mask:0xf bound_ctrl:1
	v_mov_b32_dpp v122, v118 quad_perm:[1,1,3,3] row_mask:0xf bank_mask:0xf bound_ctrl:1
	v_mov_b32_dpp v123, v119 quad_perm:[1,1,3,3] row_mask:0xf bank_mask:0xf bound_ctrl:1
	v_mov_b32_dpp v124, v121 quad_perm:[1,1,3,3] row_mask:0xf bank_mask:0xf bound_ctrl:1
	s_and_saveexec_b64 s[4:5], s[6:7]
	s_cbranch_execz .LBB0_723
	v_cvt_pk_bf16_f32 v93, v93, v94
	v_cvt_pk_bf16_f32 v94, v95, v96
	v_lshl_add_u32 v95, v53, 1, s8
	v_cvt_pk_bf16_f32 v101, v101, v104
	v_add_u32_e32 v96, 0x400, v95
	v_cvt_pk_bf16_f32 v102, v102, v106
	ds_write2_b32 v96, v94, v101 offset0:176 offset1:212
	v_add_u32_e32 v94, 0xe00, v95
	v_cvt_pk_bf16_f32 v118, v118, v122
	v_cvt_pk_bf16_f32 v117, v117, v120
	v_cvt_pk_bf16_f32 v109, v109, v110
	v_cvt_pk_bf16_f32 v110, v111, v112
	v_cvt_pk_bf16_f32 v105, v105, v108
	v_cvt_pk_bf16_f32 v103, v103, v107
	v_cvt_pk_bf16_f32 v99, v99, v100
	v_cvt_pk_bf16_f32 v97, v97, v98
	ds_write2_b32 v94, v93, v102 offset0:112 offset1:148
	v_add_u32_e32 v93, 0x1800, v95
	v_add_u32_e32 v94, 0x2000, v95
	v_add_u32_e32 v96, 0x600, v95
	v_add_u32_e32 v95, 0x1000, v95
	v_cvt_pk_bf16_f32 v121, v121, v124
	v_cvt_pk_bf16_f32 v119, v119, v123
	v_cvt_pk_bf16_f32 v115, v115, v116
	v_cvt_pk_bf16_f32 v113, v113, v114
	ds_write2_b32 v93, v97, v103 offset0:48 offset1:84
	ds_write2_b32 v94, v99, v105 offset0:112 offset1:148
	ds_write2_b32 v96, v110, v117 offset0:120 offset1:156
	ds_write2_b32 v95, v109, v118 offset0:56 offset1:92
	ds_write2_b32 v93, v113, v119 offset0:120 offset1:156
	ds_write2_b32 v94, v115, v121 offset0:184 offset1:220
	s_branch .LBB0_723

.LBB0_738:
	s_and_b64 vcc, exec, s[4:5]
	s_cbranch_vccz .LBB0_753
	v_lshlrev_b32_e32 v5, 1, v148
	s_add_i32 s4, 0, 0x19c00
	v_add_u32_e32 v2, s4, v5
	v_mov_b32_e32 v12, 0
	v_mov_b32_e32 v13, 0
	v_mov_b32_e32 v14, 0
	v_mov_b32_e32 v15, 0
	v_mov_b32_e32 v24, 0
	v_mov_b32_e32 v25, 0
	v_mov_b32_e32 v26, 0
	v_mov_b32_e32 v27, 0
	v_mov_b32_e32 v40, 0
	v_mov_b32_e32 v41, 0
	v_mov_b32_e32 v42, 0
	v_mov_b32_e32 v43, 0
	v_mov_b32_e32 v44, 0
	v_mov_b32_e32 v45, 0
	v_mov_b32_e32 v46, 0
	v_mov_b32_e32 v47, 0
	v_mov_b32_e32 v48, 0
	v_mov_b32_e32 v49, 0
	v_mov_b32_e32 v50, 0
	v_mov_b32_e32 v56, 0
	v_mov_b32_e32 v57, 0
	v_mov_b32_e32 v58, 0
	v_mov_b32_e32 v59, 0
	v_mov_b32_e32 v60, 0
	v_mov_b32_e32 v61, 0
	v_mov_b32_e32 v62, 0
	v_mov_b32_e32 v63, 0
	v_mov_b32_e32 v64, 0
	v_mov_b32_e32 v65, 0
	v_mov_b32_e32 v66, 0
	v_mov_b32_e32 v67, 0
	v_mov_b32_e32 v68, 0
	v_mov_b32_e32 v69, 0
	v_mov_b32_e32 v70, 0
	v_mov_b32_e32 v71, 0
	v_mov_b32_e32 v73, 0
	v_mov_b32_e32 v75, 0
	v_mov_b32_e32 v77, 0
	v_mov_b32_e32 v80, 0
	v_mov_b32_e32 v81, 0
	v_mov_b32_e32 v82, 0
	v_mov_b32_e32 v83, 0
	v_mov_b32_e32 v84, 0
	v_mov_b32_e32 v85, 0
	v_mov_b32_e32 v86, 0
	v_mov_b32_e32 v87, 0
	ds_read_u16_d16_hi v40, v2 offset:6656
	ds_read_u16_d16_hi v41, v2 offset:6784
	ds_read_u16_d16_hi v42, v2 offset:6912
	ds_read_u16_d16_hi v43, v2 offset:7040
	ds_read_u16_d16_hi v44, v2 offset:7168
	ds_read_u16_d16_hi v45, v2 offset:7296
	ds_read_u16_d16_hi v46, v2 offset:7424
	ds_read_u16_d16_hi v47, v2 offset:7552
	v_add_u32_e32 v3, s4, v148
	ds_read_u16_d16_hi v48, v2 offset:7680
	ds_read_u16_d16_hi v49, v2 offset:7808
	ds_read_u16_d16_hi v50, v2 offset:7936
	ds_read_u16 v51, v2 offset:8064
	ds_read_u8 v1, v3 offset:8768
	ds_read_u8 v9, v3 offset:8896
	ds_read_u8 v0, v3 offset:8832
	ds_read_u8 v8, v3 offset:8704
	ds_read_u16_d16_hi v58, v2 offset:1024
	ds_read_u16_d16_hi v12, v2 offset:3072
	ds_read_u16_d16_hi v61, v2 offset:1152
	ds_read_u16_d16_hi v13, v2 offset:3200
	ds_read_u16_d16_hi v64, v2 offset:1280
	ds_read_u16_d16_hi v14, v2 offset:3328
	ds_read_u16_d16_hi v15, v2 offset:3456
	ds_read_u16_d16_hi v67, v2 offset:1408
	ds_read_u16_d16_hi v68, v2 offset:6144
	ds_read_u16_d16_hi v69, v2 offset:6272
	ds_read_u16_d16_hi v70, v2 offset:6400
	ds_read_u16_d16_hi v71, v2 offset:6528
	ds_read_u16 v72, v2 offset:5120
	ds_read_u16 v74, v2 offset:5248
	ds_read_u16 v76, v2 offset:5376
	ds_read_u16 v78, v2 offset:5504
	s_add_i32 s4, 0, 0x1c480
	v_mov_b32_e32 v7, s4
	s_add_i32 s4, 0, 0x1c490
	v_mov_b32_e32 v3, s4
	s_add_i32 s4, 0, 0x1c4a0
	v_mov_b32_e32 v10, s4
	s_add_i32 s4, 0, 0x1c4b0
	v_mov_b32_e32 v11, s4
	ds_read_b32 v2, v7
	ds_read_b32 v3, v3
	ds_read_b32 v10, v10
	ds_read_b32 v11, v11
	v_and_b32_e32 v7, 1, v128
	v_lshrrev_b32_e32 v16, 1, v128
	v_cmp_eq_u32_e64 s[6:7], 0, v7
	v_and_b32_e32 v7, 50, v128
	v_and_b32_e32 v5, 8, v5
	v_and_b32_e32 v16, 4, v16
	v_or3_b32 v52, v16, v7, v5
	v_and_b32_e32 v5, 32, v128
	v_and_b32_e32 v7, 31, v128
	s_mov_b32 s13, 0
	v_mul_u32_u24_e32 v53, 0x50, v148
	v_mul_u32_u24_e32 v54, 48, v5
	v_mul_u32_u24_e32 v55, 48, v7
	v_mov_b32_e32 v5, v4
	v_mov_b32_e32 v7, v6
	s_mov_b32 s12, 0x3b808081
	s_waitcnt lgkmcnt(0)
	s_branch .LBB0_742
.LBB0_740:
	s_or_b64 exec, exec, s[4:5]
	v_add_f32_e32 v92, v92, v73
	v_add_f32_e32 v92, v92, v75
	v_add_f32_e32 v92, v92, v77
	v_lshlrev_b32_e32 v93, 16, v79
	v_add_f32_e32 v92, v92, v93
	v_exp_f32_e32 v92, v92
	s_nop 0
	v_pk_mul_f32 v[34:35], v[34:35], v[92:93] op_sel_hi:[1,0]
	v_pk_mul_f32 v[28:29], v[28:29], v[92:93] op_sel_hi:[1,0]
	v_pk_mul_f32 v[38:39], v[38:39], v[34:35]
	v_pk_mul_f32 v[34:35], v[34:35], v[36:37] neg_lo:[0,1] neg_hi:[0,1]
	v_pk_mul_f32 v[32:33], v[32:33], v[28:29]
	v_pk_mul_f32 v[28:29], v[28:29], v[30:31] neg_lo:[0,1] neg_hi:[0,1]
	v_add_u32_e32 v36, s8, v53
	v_cvt_pk_bf16_f32 v28, v28, v29
	v_cvt_pk_bf16_f32 v29, v34, v35
	v_cvt_pk_bf16_f32 v30, v32, v33
	v_cvt_pk_bf16_f32 v31, v38, v39
	v_add_u32_e32 v32, 0x2000, v36
	ds_write2_b64 v32, v[28:29], v[30:31] offset0:129 offset1:133
	v_lshl_or_b32 v28, v89, 16, v88
	v_lshl_or_b32 v29, v91, 16, v90
	v_add3_u32 v30, s8, v54, v55
	ds_write_b64 v30, v[28:29] offset:14344

.LBB0_742:
	s_add_i32 s16, s13, 1
	s_cmpk_lt_u32 s13, 0x200
	s_cselect_b64 s[14:15], -1, 0
	s_cmpk_gt_u32 s13, 0x1ff
	s_cbranch_scc1 .LBB0_744
	s_mul_i32 s4, s16, 0xcccd
	s_lshr_b32 s4, s4, 18
	s_mul_i32 s4, s4, 5
	s_sub_i32 s4, s16, s4
	s_and_b32 s4, s4, 0xffff
	s_mulk_i32 s4, 0x2900
	s_add_i32 s4, s4, 0
	s_add_i32 s4, s4, 0x19c00
	v_mov_b32_e32 v16, s4
	v_lshl_add_u32 v28, v148, 1, s4
	v_add_u32_e32 v20, s4, v148
	v_add_u32_e32 v18, 0x2800, v16
	ds_read_u16_d16_hi v56, v28 offset:6656
	ds_read_u16_d16_hi v57, v28 offset:6784
	ds_read_u16_d16_hi v59, v28 offset:6912
	ds_read_u16_d16_hi v60, v28 offset:7040
	ds_read_u16_d16_hi v62, v28 offset:7168
	ds_read_u16_d16_hi v63, v28 offset:7296
	ds_read_u16_d16_hi v65, v28 offset:7424
	ds_read_u16_d16_hi v66, v28 offset:7552
	ds_read2_b32 v[16:17], v18 offset0:32 offset1:36
	ds_read2_b32 v[18:19], v18 offset0:40 offset1:44
	ds_read_u16_d16_hi v73, v28 offset:7680
	ds_read_u16_d16_hi v75, v28 offset:7808
	ds_read_u16_d16_hi v77, v28 offset:7936
	ds_read_u16 v79, v28 offset:8064
	ds_read_u8 v21, v20 offset:8768
	ds_read_u8 v23, v20 offset:8896
	ds_read_u8 v22, v20 offset:8832
	ds_read_u8 v20, v20 offset:8704
	ds_read_u16_d16_hi v84, v28 offset:1024
	ds_read_u16_d16_hi v24, v28 offset:3072
	ds_read_u16_d16_hi v85, v28 offset:1152
	ds_read_u16_d16_hi v25, v28 offset:3200
	ds_read_u16_d16_hi v86, v28 offset:1280
	ds_read_u16_d16_hi v26, v28 offset:3328
	ds_read_u16_d16_hi v27, v28 offset:3456
	ds_read_u16_d16_hi v87, v28 offset:1408
	ds_read_u16_d16_hi v80, v28 offset:6144
	ds_read_u16_d16_hi v81, v28 offset:6272
	ds_read_u16_d16_hi v82, v28 offset:6400
	ds_read_u16_d16_hi v83, v28 offset:6528
	ds_read_u16 v88, v28 offset:5120
	ds_read_u16 v89, v28 offset:5248
	ds_read_u16 v90, v28 offset:5376
	ds_read_u16 v91, v28 offset:5504
.LBB0_744:
	v_cndmask_b32_e64 v28, 0, 1, s[14:15]
	v_cmp_ne_u32_e64 s[8:9], 1, v28
	s_andn2_b64 vcc, exec, s[14:15]
	s_cbranch_vccnz .LBB0_748
	v_add_f32_e32 v28, 0, v68
	v_add_f32_e32 v28, v28, v69
	v_add_f32_e32 v28, v28, v70
	v_add_f32_e32 v28, v28, v71
	v_add_f32_e32 v28, v28, v40
	v_add_f32_e32 v28, v28, v41
	v_add_f32_e32 v28, v28, v42
	v_add_f32_e32 v28, v28, v43
	v_add_f32_e32 v29, v28, v44
	v_exp_f32_e32 v39, v28
	v_exp_f32_e32 v101, v29
	v_cvt_f32_u32_e32 v35, v1
	v_cvt_f32_u32_e32 v34, v8
	v_add_f32_e32 v38, v29, v45
	v_pk_mul_f32 v[36:37], v[4:5], v[12:13]
	v_cvt_f32_u32_e32 v117, v9
	v_cvt_f32_u32_e32 v116, v0
	v_add_f32_e32 v109, v38, v46
	v_pk_mul_f32 v[36:37], v[36:37], v[2:3]
	v_exp_f32_e32 v111, v38
	v_add_f32_e32 v92, v109, v47
	v_mul_f32_e32 v95, v39, v36
	v_mul_f32_e32 v93, v101, v58
	v_pk_mul_f32 v[30:31], v[34:35], s[12:13] op_sel_hi:[1,0]
	v_pk_mul_f32 v[112:113], v[4:5], v[14:15]
	v_rcp_f32_e32 v28, v101
	v_pk_mul_f32 v[30:31], v[30:31], v[36:37]
	v_mul_f32_e32 v101, v101, v37
	v_pk_mul_f32 v[36:37], v[116:117], s[12:13] op_sel_hi:[1,0]
	v_pk_mul_f32 v[118:119], v[112:113], v[10:11]
	v_rcp_f32_e32 v29, v111
	v_mul_f32_e32 v102, v111, v61
	v_exp_f32_e32 v120, v109
	v_mul_f32_e32 v111, v111, v118
	v_pk_mul_f32 v[36:37], v[36:37], v[118:119]
	v_exp_f32_e32 v118, v92
	v_pk_fma_f32 v[34:35], v[34:35], s[12:13], -1.0 op_sel_hi:[1,0,0]
	v_pk_fma_f32 v[116:117], v[116:117], s[12:13], -1.0 op_sel_hi:[1,0,0]
	v_pk_fma_f32 v[34:35], v[6:7], v[34:35], 1.0 op_sel_hi:[1,1,0]
	v_pk_fma_f32 v[116:117], v[6:7], v[116:117], 1.0 op_sel_hi:[1,1,0]
	v_pk_mul_f32 v[32:33], v[34:35], v[12:13]
	v_rcp_f32_e32 v34, v120
	v_mul_f32_e32 v109, v120, v64
	v_rcp_f32_e32 v35, v118
	s_and_b32 s4, s13, 2
	v_pk_mul_f32 v[38:39], v[116:117], v[14:15]
	s_mulk_i32 s4, 0x5f00
	v_mul_f32_e32 v97, v28, v30
	v_mul_f32_e32 v99, v28, v32
	v_mul_f32_e32 v103, v29, v31
	v_mul_f32_e32 v105, v29, v33
	v_mul_f32_e32 v113, v34, v36
	v_mul_f32_e32 v115, v34, v38
	v_mul_f32_e32 v117, v120, v119
	v_mul_f32_e32 v118, v118, v67
	v_mul_f32_e32 v119, v35, v37
	v_mul_f32_e32 v121, v35, v39
	s_add_i32 s14, s4, 0
	v_mov_b32_dpp v94, v93 quad_perm:[1,1,3,3] row_mask:0xf bank_mask:0xf bound_ctrl:1
	v_mov_b32_dpp v96, v95 quad_perm:[1,1,3,3] row_mask:0xf bank_mask:0xf bound_ctrl:1
	v_mov_b32_dpp v98, v97 quad_perm:[1,1,3,3] row_mask:0xf bank_mask:0xf bound_ctrl:1
	v_mov_b32_dpp v100, v99 quad_perm:[1,1,3,3] row_mask:0xf bank_mask:0xf bound_ctrl:1
	v_mov_b32_dpp v104, v101 quad_perm:[1,1,3,3] row_mask:0xf bank_mask:0xf bound_ctrl:1
	v_mov_b32_dpp v106, v102 quad_perm:[1,1,3,3] row_mask:0xf bank_mask:0xf bound_ctrl:1
	v_mov_b32_dpp v107, v103 quad_perm:[1,1,3,3] row_mask:0xf bank_mask:0xf bound_ctrl:1
	v_mov_b32_dpp v108, v105 quad_perm:[1,1,3,3] row_mask:0xf bank_mask:0xf bound_ctrl:1
	v_mov_b32_dpp v110, v109 quad_perm:[1,1,3,3] row_mask:0xf bank_mask:0xf bound_ctrl:1
	v_mov_b32_dpp v112, v111 quad_perm:[1,1,3,3] row_mask:0xf bank_mask:0xf bound_ctrl:1
	v_mov_b32_dpp v114, v113 quad_perm:[1,1,3,3] row_mask:0xf bank_mask:0xf bound_ctrl:1
	v_mov_b32_dpp v116, v115 quad_perm:[1,1,3,3] row_mask:0xf bank_mask:0xf bound_ctrl:1
	v_mov_b32_dpp v120, v117 quad_perm:[1,1,3,3] row_mask:0xf bank_mask:0xf bound_ctrl:1
	v_mov_b32_dpp v122, v118 quad_perm:[1,1,3,3] row_mask:0xf bank_mask:0xf bound_ctrl:1
	v_mov_b32_dpp v123, v119 quad_perm:[1,1,3,3] row_mask:0xf bank_mask:0xf bound_ctrl:1
	v_mov_b32_dpp v124, v121 quad_perm:[1,1,3,3] row_mask:0xf bank_mask:0xf bound_ctrl:1
	s_and_saveexec_b64 s[4:5], s[6:7]
	s_cbranch_execz .LBB0_747
	v_cvt_pk_bf16_f32 v93, v93, v94
	v_cvt_pk_bf16_f32 v94, v95, v96
	v_lshl_add_u32 v95, v52, 1, s14
	v_cvt_pk_bf16_f32 v101, v101, v104
	v_add_u32_e32 v96, 0x400, v95
	v_cvt_pk_bf16_f32 v102, v102, v106
	ds_write2_b32 v96, v94, v101 offset0:32 offset1:68
	v_add_u32_e32 v94, 0xc00, v95
	v_cvt_pk_bf16_f32 v103, v103, v107
	v_cvt_pk_bf16_f32 v97, v97, v98
	ds_write2_b32 v94, v93, v102 offset0:96 offset1:132
	v_add_u32_e32 v93, 0x1400, v95
	v_cvt_pk_bf16_f32 v105, v105, v108
	v_cvt_pk_bf16_f32 v99, v99, v100
	ds_write2_b32 v93, v97, v103 offset0:160 offset1:196
	v_add_u32_e32 v93, 0x1e00, v95
	v_cvt_pk_bf16_f32 v119, v119, v123
	v_cvt_pk_bf16_f32 v118, v118, v122
	v_cvt_pk_bf16_f32 v117, v117, v120
	v_cvt_pk_bf16_f32 v113, v113, v114
	v_cvt_pk_bf16_f32 v109, v109, v110
	v_cvt_pk_bf16_f32 v110, v111, v112
	ds_write2_b32 v93, v99, v105 offset0:96 offset1:132
	ds_write2_b32 v96, v110, v117 offset0:104 offset1:140
	ds_write2_b32 v94, v109, v118 offset0:168 offset1:204
	v_add_u32_e32 v93, 0x1600, v95
	v_cvt_pk_bf16_f32 v121, v121, v124
	v_cvt_pk_bf16_f32 v115, v115, v116
	ds_write2_b32 v93, v113, v119 offset0:104 offset1:140
	v_add_u32_e32 v93, 0x2000, v95
	ds_write2_b32 v93, v115, v121 offset0:40 offset1:76
.LBB0_747:
	s_or_b64 exec, exec, s[4:5]
	v_add_f32_e32 v92, v92, v48
	v_add_f32_e32 v92, v92, v49
	v_add_f32_e32 v92, v92, v50
	v_lshlrev_b32_e32 v93, 16, v51
	v_add_f32_e32 v92, v92, v93
	v_exp_f32_e32 v92, v92
	s_nop 0
	v_pk_mul_f32 v[34:35], v[34:35], v[92:93] op_sel_hi:[1,0]
	v_pk_mul_f32 v[28:29], v[28:29], v[92:93] op_sel_hi:[1,0]
	v_pk_mul_f32 v[38:39], v[34:35], v[38:39]
	v_pk_mul_f32 v[34:35], v[34:35], v[36:37] neg_lo:[0,1] neg_hi:[0,1]
	v_pk_mul_f32 v[32:33], v[28:29], v[32:33]
	v_pk_mul_f32 v[28:29], v[28:29], v[30:31] neg_lo:[0,1] neg_hi:[0,1]
	v_add_u32_e32 v36, s14, v53
	v_cvt_pk_bf16_f32 v28, v28, v29
	v_cvt_pk_bf16_f32 v29, v34, v35
	v_cvt_pk_bf16_f32 v30, v32, v33
	v_cvt_pk_bf16_f32 v31, v38, v39
	v_add_u32_e32 v32, 0x2000, v36
	ds_write2_b64 v32, v[28:29], v[30:31] offset0:129 offset1:133
	v_lshl_or_b32 v28, v74, 16, v72
	v_lshl_or_b32 v29, v78, 16, v76
	v_add3_u32 v30, s14, v54, v55
	ds_write_b64 v30, v[28:29] offset:14344
.LBB0_748:
	s_waitcnt lgkmcnt(0)
	s_barrier
	s_add_i32 s14, s13, 2
	s_cmpk_gt_u32 s13, 0x1fd
	s_cbranch_scc1 .LBB0_750
	s_mul_i32 s4, s14, 0xcccd
	s_lshr_b32 s4, s4, 18
	s_mul_i32 s4, s4, 5
	s_sub_i32 s4, s14, s4
	s_and_b32 s4, s4, 0xffff
	s_mulk_i32 s4, 0x2900
	s_add_i32 s4, s4, 0
	s_add_i32 s4, s4, 0x19c00
	v_mov_b32_e32 v0, s4
	v_lshl_add_u32 v28, v148, 1, s4
	v_add_u32_e32 v8, s4, v148
	v_add_u32_e32 v0, 0x2800, v0
	ds_read_u16_d16_hi v40, v28 offset:6656
	ds_read_u16_d16_hi v41, v28 offset:6784
	ds_read_u16_d16_hi v42, v28 offset:6912
	ds_read_u16_d16_hi v43, v28 offset:7040
	ds_read_u16_d16_hi v44, v28 offset:7168
	ds_read_u16_d16_hi v45, v28 offset:7296
	ds_read_u16_d16_hi v46, v28 offset:7424
	ds_read_u16_d16_hi v47, v28 offset:7552
	ds_read2_b32 v[2:3], v0 offset0:32 offset1:36
	ds_read2_b32 v[10:11], v0 offset0:40 offset1:44
	ds_read_u16_d16_hi v48, v28 offset:7680
	ds_read_u16_d16_hi v49, v28 offset:7808
	ds_read_u16_d16_hi v50, v28 offset:7936
	ds_read_u16 v51, v28 offset:8064
	ds_read_u8 v1, v8 offset:8768
	ds_read_u8 v9, v8 offset:8896
	ds_read_u8 v0, v8 offset:8832
	ds_read_u8 v8, v8 offset:8704
	ds_read_u16_d16_hi v58, v28 offset:1024
	ds_read_u16_d16_hi v12, v28 offset:3072
	ds_read_u16_d16_hi v61, v28 offset:1152
	ds_read_u16_d16_hi v13, v28 offset:3200
	ds_read_u16_d16_hi v64, v28 offset:1280
	ds_read_u16_d16_hi v14, v28 offset:3328
	ds_read_u16_d16_hi v15, v28 offset:3456
	ds_read_u16_d16_hi v67, v28 offset:1408
	ds_read_u16_d16_hi v68, v28 offset:6144
	ds_read_u16_d16_hi v69, v28 offset:6272
	ds_read_u16_d16_hi v70, v28 offset:6400
	ds_read_u16_d16_hi v71, v28 offset:6528
	ds_read_u16 v72, v28 offset:5120
	ds_read_u16 v74, v28 offset:5248
	ds_read_u16 v76, v28 offset:5376
	ds_read_u16 v78, v28 offset:5504
.LBB0_750:
	s_and_b64 vcc, exec, s[8:9]
	s_cbranch_vccnz .LBB0_741
	v_add_f32_e32 v28, 0, v80
	v_add_f32_e32 v28, v28, v81
	v_add_f32_e32 v28, v28, v82
	v_add_f32_e32 v28, v28, v83
	v_add_f32_e32 v28, v28, v56
	v_add_f32_e32 v28, v28, v57
	v_add_f32_e32 v28, v28, v59
	v_add_f32_e32 v28, v28, v60
	v_add_f32_e32 v29, v28, v62
	v_exp_f32_e32 v39, v28
	v_exp_f32_e32 v101, v29
	v_cvt_f32_u32_e32 v35, v21
	v_cvt_f32_u32_e32 v34, v20
	v_add_f32_e32 v38, v29, v63
	v_pk_mul_f32 v[36:37], v[4:5], v[24:25]
	v_cvt_f32_u32_e32 v117, v23
	v_cvt_f32_u32_e32 v116, v22
	v_add_f32_e32 v109, v38, v65
	v_pk_mul_f32 v[36:37], v[16:17], v[36:37]
	v_exp_f32_e32 v111, v38
	v_add_f32_e32 v92, v109, v66
	v_mul_f32_e32 v95, v36, v39
	v_mul_f32_e32 v93, v101, v84
	v_pk_mul_f32 v[30:31], v[34:35], s[12:13] op_sel_hi:[1,0]
	v_pk_mul_f32 v[112:113], v[4:5], v[26:27]
	v_rcp_f32_e32 v28, v101
	v_pk_mul_f32 v[30:31], v[30:31], v[36:37]
	v_mul_f32_e32 v101, v37, v101
	v_pk_mul_f32 v[36:37], v[116:117], s[12:13] op_sel_hi:[1,0]
	v_pk_mul_f32 v[118:119], v[18:19], v[112:113]
	v_rcp_f32_e32 v29, v111
	v_mul_f32_e32 v102, v111, v85
	v_exp_f32_e32 v120, v109
	v_mul_f32_e32 v111, v118, v111
	v_pk_mul_f32 v[36:37], v[36:37], v[118:119]
	v_exp_f32_e32 v118, v92
	v_pk_fma_f32 v[34:35], v[34:35], s[12:13], -1.0 op_sel_hi:[1,0,0]
	v_pk_fma_f32 v[116:117], v[116:117], s[12:13], -1.0 op_sel_hi:[1,0,0]
	v_pk_fma_f32 v[34:35], v[6:7], v[34:35], 1.0 op_sel_hi:[1,1,0]
	v_pk_fma_f32 v[116:117], v[6:7], v[116:117], 1.0 op_sel_hi:[1,1,0]
	v_pk_mul_f32 v[32:33], v[34:35], v[24:25]
	v_rcp_f32_e32 v34, v120
	v_mul_f32_e32 v109, v120, v86
	v_rcp_f32_e32 v35, v118
	s_and_b32 s4, s16, 3
	v_pk_mul_f32 v[38:39], v[116:117], v[26:27]
	s_mulk_i32 s4, 0x5f00
	v_mul_f32_e32 v97, v30, v28
	v_mul_f32_e32 v99, v32, v28
	v_mul_f32_e32 v103, v31, v29
	v_mul_f32_e32 v105, v33, v29
	v_mul_f32_e32 v113, v36, v34
	v_mul_f32_e32 v115, v38, v34
	v_mul_f32_e32 v117, v119, v120
	v_mul_f32_e32 v118, v118, v87
	v_mul_f32_e32 v119, v37, v35
	v_mul_f32_e32 v121, v39, v35
	s_add_i32 s8, s4, 0
	v_mov_b32_dpp v94, v93 quad_perm:[1,1,3,3] row_mask:0xf bank_mask:0xf bound_ctrl:1
	v_mov_b32_dpp v96, v95 quad_perm:[1,1,3,3] row_mask:0xf bank_mask:0xf bound_ctrl:1
	v_mov_b32_dpp v98, v97 quad_perm:[1,1,3,3] row_mask:0xf bank_mask:0xf bound_ctrl:1
	v_mov_b32_dpp v100, v99 quad_perm:[1,1,3,3] row_mask:0xf bank_mask:0xf bound_ctrl:1
	v_mov_b32_dpp v104, v101 quad_perm:[1,1,3,3] row_mask:0xf bank_mask:0xf bound_ctrl:1
	v_mov_b32_dpp v106, v102 quad_perm:[1,1,3,3] row_mask:0xf bank_mask:0xf bound_ctrl:1
	v_mov_b32_dpp v107, v103 quad_perm:[1,1,3,3] row_mask:0xf bank_mask:0xf bound_ctrl:1
	v_mov_b32_dpp v108, v105 quad_perm:[1,1,3,3] row_mask:0xf bank_mask:0xf bound_ctrl:1
	v_mov_b32_dpp v110, v109 quad_perm:[1,1,3,3] row_mask:0xf bank_mask:0xf bound_ctrl:1
	v_mov_b32_dpp v112, v111 quad_perm:[1,1,3,3] row_mask:0xf bank_mask:0xf bound_ctrl:1
	v_mov_b32_dpp v114, v113 quad_perm:[1,1,3,3] row_mask:0xf bank_mask:0xf bound_ctrl:1
	v_mov_b32_dpp v116, v115 quad_perm:[1,1,3,3] row_mask:0xf bank_mask:0xf bound_ctrl:1
	v_mov_b32_dpp v120, v117 quad_perm:[1,1,3,3] row_mask:0xf bank_mask:0xf bound_ctrl:1
	v_mov_b32_dpp v122, v118 quad_perm:[1,1,3,3] row_mask:0xf bank_mask:0xf bound_ctrl:1
	v_mov_b32_dpp v123, v119 quad_perm:[1,1,3,3] row_mask:0xf bank_mask:0xf bound_ctrl:1
	v_mov_b32_dpp v124, v121 quad_perm:[1,1,3,3] row_mask:0xf bank_mask:0xf bound_ctrl:1
	s_and_saveexec_b64 s[4:5], s[6:7]
	s_cbranch_execz .LBB0_740
	v_cvt_pk_bf16_f32 v93, v93, v94
	v_cvt_pk_bf16_f32 v94, v95, v96
	v_lshl_add_u32 v95, v52, 1, s8
	v_cvt_pk_bf16_f32 v101, v101, v104
	v_add_u32_e32 v96, 0x400, v95
	v_cvt_pk_bf16_f32 v102, v102, v106
	ds_write2_b32 v96, v94, v101 offset0:32 offset1:68
	v_add_u32_e32 v94, 0xc00, v95
	v_cvt_pk_bf16_f32 v103, v103, v107
	v_cvt_pk_bf16_f32 v97, v97, v98
	ds_write2_b32 v94, v93, v102 offset0:96 offset1:132
	v_add_u32_e32 v93, 0x1400, v95
	v_cvt_pk_bf16_f32 v105, v105, v108
	v_cvt_pk_bf16_f32 v99, v99, v100
	ds_write2_b32 v93, v97, v103 offset0:160 offset1:196
	v_add_u32_e32 v93, 0x1e00, v95
	v_cvt_pk_bf16_f32 v119, v119, v123
	v_cvt_pk_bf16_f32 v118, v118, v122
	v_cvt_pk_bf16_f32 v117, v117, v120
	v_cvt_pk_bf16_f32 v113, v113, v114
	v_cvt_pk_bf16_f32 v109, v109, v110
	v_cvt_pk_bf16_f32 v110, v111, v112
	ds_write2_b32 v93, v99, v105 offset0:96 offset1:132
	ds_write2_b32 v96, v110, v117 offset0:104 offset1:140
	ds_write2_b32 v94, v109, v118 offset0:168 offset1:204
	v_add_u32_e32 v93, 0x1600, v95
	v_cvt_pk_bf16_f32 v121, v121, v124
	v_cvt_pk_bf16_f32 v115, v115, v116
	ds_write2_b32 v93, v113, v119 offset0:104 offset1:140
	v_add_u32_e32 v93, 0x2000, v95
	ds_write2_b32 v93, v115, v121 offset0:40 offset1:76
	s_branch .LBB0_740

.LBB0_754:
	s_and_b64 vcc, exec, s[4:5]
	s_cbranch_vccz .LBB0_769
	v_lshlrev_b32_e32 v5, 1, v148
	s_add_i32 s4, 0, 0x19c00
	v_add_u32_e32 v2, s4, v5
	v_mov_b32_e32 v12, 0
	v_mov_b32_e32 v13, 0
	v_mov_b32_e32 v14, 0
	v_mov_b32_e32 v15, 0
	v_mov_b32_e32 v24, 0
	v_mov_b32_e32 v25, 0
	v_mov_b32_e32 v26, 0
	v_mov_b32_e32 v27, 0
	v_mov_b32_e32 v40, 0
	v_mov_b32_e32 v41, 0
	v_mov_b32_e32 v42, 0
	v_mov_b32_e32 v43, 0
	v_mov_b32_e32 v44, 0
	v_mov_b32_e32 v45, 0
	v_mov_b32_e32 v46, 0
	v_mov_b32_e32 v47, 0
	v_mov_b32_e32 v48, 0
	v_mov_b32_e32 v49, 0
	v_mov_b32_e32 v50, 0
	v_mov_b32_e32 v56, 0
	v_mov_b32_e32 v57, 0
	v_mov_b32_e32 v58, 0
	v_mov_b32_e32 v59, 0
	v_mov_b32_e32 v60, 0
	v_mov_b32_e32 v61, 0
	v_mov_b32_e32 v62, 0
	v_mov_b32_e32 v63, 0
	v_mov_b32_e32 v64, 0
	v_mov_b32_e32 v65, 0
	v_mov_b32_e32 v66, 0
	v_mov_b32_e32 v67, 0
	v_mov_b32_e32 v68, 0
	v_mov_b32_e32 v69, 0
	v_mov_b32_e32 v70, 0
	v_mov_b32_e32 v71, 0
	v_mov_b32_e32 v73, 0
	v_mov_b32_e32 v75, 0
	v_mov_b32_e32 v77, 0
	v_mov_b32_e32 v80, 0
	v_mov_b32_e32 v81, 0
	v_mov_b32_e32 v82, 0
	v_mov_b32_e32 v83, 0
	v_mov_b32_e32 v84, 0
	v_mov_b32_e32 v85, 0
	v_mov_b32_e32 v86, 0
	v_mov_b32_e32 v87, 0
	ds_read_u16_d16_hi v40, v2 offset:6656
	ds_read_u16_d16_hi v41, v2 offset:6784
	ds_read_u16_d16_hi v42, v2 offset:6912
	ds_read_u16_d16_hi v43, v2 offset:7040
	ds_read_u16_d16_hi v44, v2 offset:7168
	ds_read_u16_d16_hi v45, v2 offset:7296
	ds_read_u16_d16_hi v46, v2 offset:7424
	ds_read_u16_d16_hi v47, v2 offset:7552
	v_add_u32_e32 v3, s4, v148
	ds_read_u16_d16_hi v48, v2 offset:7680
	ds_read_u16_d16_hi v49, v2 offset:7808
	ds_read_u16_d16_hi v50, v2 offset:7936
	ds_read_u16 v51, v2 offset:8064
	ds_read_u8 v1, v3 offset:8512
	ds_read_u8 v9, v3 offset:8640
	ds_read_u8 v0, v3 offset:8576
	ds_read_u8 v8, v3 offset:8448
	ds_read_u16_d16_hi v58, v2 offset:512
	ds_read_u16_d16_hi v12, v2 offset:2560
	ds_read_u16_d16_hi v61, v2 offset:640
	ds_read_u16_d16_hi v13, v2 offset:2688
	ds_read_u16_d16_hi v64, v2 offset:768
	ds_read_u16_d16_hi v14, v2 offset:2816
	ds_read_u16_d16_hi v15, v2 offset:2944
	ds_read_u16_d16_hi v67, v2 offset:896
	ds_read_u16_d16_hi v68, v2 offset:6144
	ds_read_u16_d16_hi v69, v2 offset:6272
	ds_read_u16_d16_hi v70, v2 offset:6400
	ds_read_u16_d16_hi v71, v2 offset:6528
	ds_read_u16 v72, v2 offset:4608
	ds_read_u16 v74, v2 offset:4736
	ds_read_u16 v76, v2 offset:4864
	ds_read_u16 v78, v2 offset:4992
	s_add_i32 s4, 0, 0x1c440
	v_mov_b32_e32 v7, s4
	s_add_i32 s4, 0, 0x1c450
	v_mov_b32_e32 v3, s4
	s_add_i32 s4, 0, 0x1c460
	v_mov_b32_e32 v10, s4
	s_add_i32 s4, 0, 0x1c470
	v_mov_b32_e32 v11, s4
	ds_read_b32 v2, v7
	ds_read_b32 v3, v3
	ds_read_b32 v10, v10
	ds_read_b32 v11, v11
	v_and_b32_e32 v7, 1, v128
	v_lshrrev_b32_e32 v16, 1, v128
	v_cmp_eq_u32_e64 s[6:7], 0, v7
	v_and_b32_e32 v7, 50, v128
	v_and_b32_e32 v5, 8, v5
	v_and_b32_e32 v16, 4, v16
	v_or3_b32 v52, v16, v7, v5
	v_and_b32_e32 v5, 32, v128
	v_and_b32_e32 v7, 31, v128
	s_mov_b32 s13, 0
	v_mul_u32_u24_e32 v53, 0x50, v148
	v_mul_u32_u24_e32 v54, 48, v5
	v_mul_u32_u24_e32 v55, 48, v7
	v_mov_b32_e32 v5, v4
	v_mov_b32_e32 v7, v6
	s_mov_b32 s12, 0x3b808081
	s_waitcnt lgkmcnt(0)
	s_branch .LBB0_758
.LBB0_756:
	s_or_b64 exec, exec, s[4:5]
	v_add_f32_e32 v92, v92, v62
	v_add_f32_e32 v92, v92, v63
	v_add_f32_e32 v92, v92, v65
	v_add_f32_e32 v92, v92, v66
	v_add_f32_e32 v92, v92, v73
	v_add_f32_e32 v92, v92, v75
	v_add_f32_e32 v92, v92, v77
	v_lshlrev_b32_e32 v93, 16, v79
	v_add_f32_e32 v92, v92, v93
	v_exp_f32_e32 v92, v92
	s_nop 0
	v_pk_mul_f32 v[34:35], v[34:35], v[92:93] op_sel_hi:[1,0]
	v_pk_mul_f32 v[28:29], v[28:29], v[92:93] op_sel_hi:[1,0]
	v_pk_mul_f32 v[38:39], v[38:39], v[34:35]
	v_pk_mul_f32 v[34:35], v[34:35], v[36:37] neg_lo:[0,1] neg_hi:[0,1]
	v_pk_mul_f32 v[32:33], v[32:33], v[28:29]
	v_pk_mul_f32 v[28:29], v[28:29], v[30:31] neg_lo:[0,1] neg_hi:[0,1]
	v_add_u32_e32 v36, s8, v53
	v_cvt_pk_bf16_f32 v28, v28, v29
	v_cvt_pk_bf16_f32 v29, v34, v35
	v_cvt_pk_bf16_f32 v30, v32, v33
	v_cvt_pk_bf16_f32 v31, v38, v39
	v_add_u32_e32 v32, 0x2000, v36
	ds_write2_b64 v32, v[28:29], v[30:31] offset0:130 offset1:134
	v_lshl_or_b32 v28, v89, 16, v88
	v_lshl_or_b32 v29, v91, 16, v90
	v_add3_u32 v30, s8, v54, v55
	ds_write_b64 v30, v[28:29] offset:14352

.LBB0_758:
	s_add_i32 s16, s13, 1
	s_cmpk_lt_u32 s13, 0x200
	s_cselect_b64 s[14:15], -1, 0
	s_cmpk_gt_u32 s13, 0x1ff
	s_cbranch_scc1 .LBB0_760
	s_mul_i32 s4, s16, 0xcccd
	s_lshr_b32 s4, s4, 18
	s_mul_i32 s4, s4, 5
	s_sub_i32 s4, s16, s4
	s_and_b32 s4, s4, 0xffff
	s_mulk_i32 s4, 0x2900
	s_add_i32 s4, s4, 0
	s_add_i32 s4, s4, 0x19c00
	v_mov_b32_e32 v16, s4
	v_lshl_add_u32 v28, v148, 1, s4
	v_add_u32_e32 v20, s4, v148
	v_add_u32_e32 v18, 0x2800, v16
	ds_read_u16_d16_hi v56, v28 offset:6656
	ds_read_u16_d16_hi v57, v28 offset:6784
	ds_read_u16_d16_hi v59, v28 offset:6912
	ds_read_u16_d16_hi v60, v28 offset:7040
	ds_read_u16_d16_hi v62, v28 offset:7168
	ds_read_u16_d16_hi v63, v28 offset:7296
	ds_read_u16_d16_hi v65, v28 offset:7424
	ds_read_u16_d16_hi v66, v28 offset:7552
	ds_read2_b32 v[16:17], v18 offset0:16 offset1:20
	ds_read2_b32 v[18:19], v18 offset0:24 offset1:28
	ds_read_u16_d16_hi v73, v28 offset:7680
	ds_read_u16_d16_hi v75, v28 offset:7808
	ds_read_u16_d16_hi v77, v28 offset:7936
	ds_read_u16 v79, v28 offset:8064
	ds_read_u8 v21, v20 offset:8512
	ds_read_u8 v23, v20 offset:8640
	ds_read_u8 v22, v20 offset:8576
	ds_read_u8 v20, v20 offset:8448
	ds_read_u16_d16_hi v84, v28 offset:512
	ds_read_u16_d16_hi v24, v28 offset:2560
	ds_read_u16_d16_hi v85, v28 offset:640
	ds_read_u16_d16_hi v25, v28 offset:2688
	ds_read_u16_d16_hi v86, v28 offset:768
	ds_read_u16_d16_hi v26, v28 offset:2816
	ds_read_u16_d16_hi v27, v28 offset:2944
	ds_read_u16_d16_hi v87, v28 offset:896
	ds_read_u16_d16_hi v80, v28 offset:6144
	ds_read_u16_d16_hi v81, v28 offset:6272
	ds_read_u16_d16_hi v82, v28 offset:6400
	ds_read_u16_d16_hi v83, v28 offset:6528
	ds_read_u16 v88, v28 offset:4608
	ds_read_u16 v89, v28 offset:4736
	ds_read_u16 v90, v28 offset:4864
	ds_read_u16 v91, v28 offset:4992
.LBB0_760:
	v_cndmask_b32_e64 v28, 0, 1, s[14:15]
	v_cmp_ne_u32_e64 s[8:9], 1, v28
	s_andn2_b64 vcc, exec, s[14:15]
	s_cbranch_vccnz .LBB0_764
	v_add_f32_e32 v28, 0, v68
	v_add_f32_e32 v28, v28, v69
	v_add_f32_e32 v28, v28, v70
	v_add_f32_e32 v28, v28, v71
	v_add_f32_e32 v29, v28, v40
	v_exp_f32_e32 v39, v28
	v_exp_f32_e32 v101, v29
	v_cvt_f32_u32_e32 v35, v1
	v_cvt_f32_u32_e32 v34, v8
	v_add_f32_e32 v38, v29, v41
	v_pk_mul_f32 v[36:37], v[4:5], v[12:13]
	v_cvt_f32_u32_e32 v117, v9
	v_cvt_f32_u32_e32 v116, v0
	v_add_f32_e32 v109, v38, v42
	v_pk_mul_f32 v[36:37], v[36:37], v[2:3]
	v_exp_f32_e32 v111, v38
	v_add_f32_e32 v92, v109, v43
	v_mul_f32_e32 v95, v39, v36
	v_mul_f32_e32 v93, v101, v58
	v_pk_mul_f32 v[30:31], v[34:35], s[12:13] op_sel_hi:[1,0]
	v_pk_mul_f32 v[112:113], v[4:5], v[14:15]
	v_rcp_f32_e32 v28, v101
	v_pk_mul_f32 v[30:31], v[30:31], v[36:37]
	v_mul_f32_e32 v101, v101, v37
	v_pk_mul_f32 v[36:37], v[116:117], s[12:13] op_sel_hi:[1,0]
	v_pk_mul_f32 v[118:119], v[112:113], v[10:11]
	v_rcp_f32_e32 v29, v111
	v_mul_f32_e32 v102, v111, v61
	v_exp_f32_e32 v120, v109
	v_mul_f32_e32 v111, v111, v118
	v_pk_mul_f32 v[36:37], v[36:37], v[118:119]
	v_exp_f32_e32 v118, v92
	v_pk_fma_f32 v[34:35], v[34:35], s[12:13], -1.0 op_sel_hi:[1,0,0]
	v_pk_fma_f32 v[116:117], v[116:117], s[12:13], -1.0 op_sel_hi:[1,0,0]
	v_pk_fma_f32 v[34:35], v[6:7], v[34:35], 1.0 op_sel_hi:[1,1,0]
	v_pk_fma_f32 v[116:117], v[6:7], v[116:117], 1.0 op_sel_hi:[1,1,0]
	v_pk_mul_f32 v[32:33], v[34:35], v[12:13]
	v_rcp_f32_e32 v34, v120
	v_mul_f32_e32 v109, v120, v64
	v_rcp_f32_e32 v35, v118
	s_and_b32 s4, s13, 2
	v_pk_mul_f32 v[38:39], v[116:117], v[14:15]
	s_mulk_i32 s4, 0x5f00
	v_mul_f32_e32 v97, v28, v30
	v_mul_f32_e32 v99, v28, v32
	v_mul_f32_e32 v103, v29, v31
	v_mul_f32_e32 v105, v29, v33
	v_mul_f32_e32 v113, v34, v36
	v_mul_f32_e32 v115, v34, v38
	v_mul_f32_e32 v117, v120, v119
	v_mul_f32_e32 v118, v118, v67
	v_mul_f32_e32 v119, v35, v37
	v_mul_f32_e32 v121, v35, v39
	s_add_i32 s14, s4, 0
	v_mov_b32_dpp v94, v93 quad_perm:[1,1,3,3] row_mask:0xf bank_mask:0xf bound_ctrl:1
	v_mov_b32_dpp v96, v95 quad_perm:[1,1,3,3] row_mask:0xf bank_mask:0xf bound_ctrl:1
	v_mov_b32_dpp v98, v97 quad_perm:[1,1,3,3] row_mask:0xf bank_mask:0xf bound_ctrl:1
	v_mov_b32_dpp v100, v99 quad_perm:[1,1,3,3] row_mask:0xf bank_mask:0xf bound_ctrl:1
	v_mov_b32_dpp v104, v101 quad_perm:[1,1,3,3] row_mask:0xf bank_mask:0xf bound_ctrl:1
	v_mov_b32_dpp v106, v102 quad_perm:[1,1,3,3] row_mask:0xf bank_mask:0xf bound_ctrl:1
	v_mov_b32_dpp v107, v103 quad_perm:[1,1,3,3] row_mask:0xf bank_mask:0xf bound_ctrl:1
	v_mov_b32_dpp v108, v105 quad_perm:[1,1,3,3] row_mask:0xf bank_mask:0xf bound_ctrl:1
	v_mov_b32_dpp v110, v109 quad_perm:[1,1,3,3] row_mask:0xf bank_mask:0xf bound_ctrl:1
	v_mov_b32_dpp v112, v111 quad_perm:[1,1,3,3] row_mask:0xf bank_mask:0xf bound_ctrl:1
	v_mov_b32_dpp v114, v113 quad_perm:[1,1,3,3] row_mask:0xf bank_mask:0xf bound_ctrl:1
	v_mov_b32_dpp v116, v115 quad_perm:[1,1,3,3] row_mask:0xf bank_mask:0xf bound_ctrl:1
	v_mov_b32_dpp v120, v117 quad_perm:[1,1,3,3] row_mask:0xf bank_mask:0xf bound_ctrl:1
	v_mov_b32_dpp v122, v118 quad_perm:[1,1,3,3] row_mask:0xf bank_mask:0xf bound_ctrl:1
	v_mov_b32_dpp v123, v119 quad_perm:[1,1,3,3] row_mask:0xf bank_mask:0xf bound_ctrl:1
	v_mov_b32_dpp v124, v121 quad_perm:[1,1,3,3] row_mask:0xf bank_mask:0xf bound_ctrl:1
	s_and_saveexec_b64 s[4:5], s[6:7]
	s_cbranch_execz .LBB0_763
	v_cvt_pk_bf16_f32 v101, v101, v104
	v_cvt_pk_bf16_f32 v93, v93, v94
	v_cvt_pk_bf16_f32 v94, v95, v96
	v_lshl_add_u32 v95, v52, 1, s14
	v_cvt_pk_bf16_f32 v102, v102, v106
	ds_write2_b32 v95, v94, v101 offset0:144 offset1:180
	v_add_u32_e32 v94, 0x800, v95
	v_cvt_pk_bf16_f32 v105, v105, v108
	v_cvt_pk_bf16_f32 v103, v103, v107
	v_cvt_pk_bf16_f32 v99, v99, v100
	v_cvt_pk_bf16_f32 v97, v97, v98
	ds_write2_b32 v94, v93, v102 offset0:208 offset1:244
	v_add_u32_e32 v93, 0x1400, v95
	v_add_u32_e32 v94, 0x1c00, v95
	v_cvt_pk_bf16_f32 v118, v118, v122
	v_cvt_pk_bf16_f32 v117, v117, v120
	v_cvt_pk_bf16_f32 v109, v109, v110
	v_cvt_pk_bf16_f32 v110, v111, v112
	ds_write2_b32 v93, v97, v103 offset0:16 offset1:52
	ds_write2_b32 v94, v99, v105 offset0:80 offset1:116
	ds_write2_b32 v95, v110, v117 offset0:216 offset1:252
	v_add_u32_e32 v95, 0xc00, v95
	v_cvt_pk_bf16_f32 v121, v121, v124
	v_cvt_pk_bf16_f32 v119, v119, v123
	v_cvt_pk_bf16_f32 v115, v115, v116
	v_cvt_pk_bf16_f32 v113, v113, v114
	ds_write2_b32 v95, v109, v118 offset0:24 offset1:60
	ds_write2_b32 v93, v113, v119 offset0:88 offset1:124
	ds_write2_b32 v94, v115, v121 offset0:152 offset1:188
.LBB0_763:
	s_or_b64 exec, exec, s[4:5]
	v_add_f32_e32 v92, v92, v44
	v_add_f32_e32 v92, v92, v45
	v_add_f32_e32 v92, v92, v46
	v_add_f32_e32 v92, v92, v47
	v_add_f32_e32 v92, v92, v48
	v_add_f32_e32 v92, v92, v49
	v_add_f32_e32 v92, v92, v50
	v_lshlrev_b32_e32 v93, 16, v51
	v_add_f32_e32 v92, v92, v93
	v_exp_f32_e32 v92, v92
	s_nop 0
	v_pk_mul_f32 v[34:35], v[34:35], v[92:93] op_sel_hi:[1,0]
	v_pk_mul_f32 v[28:29], v[28:29], v[92:93] op_sel_hi:[1,0]
	v_pk_mul_f32 v[38:39], v[34:35], v[38:39]
	v_pk_mul_f32 v[34:35], v[34:35], v[36:37] neg_lo:[0,1] neg_hi:[0,1]
	v_pk_mul_f32 v[32:33], v[28:29], v[32:33]
	v_pk_mul_f32 v[28:29], v[28:29], v[30:31] neg_lo:[0,1] neg_hi:[0,1]
	v_add_u32_e32 v36, s14, v53
	v_cvt_pk_bf16_f32 v28, v28, v29
	v_cvt_pk_bf16_f32 v29, v34, v35
	v_cvt_pk_bf16_f32 v30, v32, v33
	v_cvt_pk_bf16_f32 v31, v38, v39
	v_add_u32_e32 v32, 0x2000, v36
	ds_write2_b64 v32, v[28:29], v[30:31] offset0:130 offset1:134
	v_lshl_or_b32 v28, v74, 16, v72
	v_lshl_or_b32 v29, v78, 16, v76
	v_add3_u32 v30, s14, v54, v55
	ds_write_b64 v30, v[28:29] offset:14352
.LBB0_764:
	s_waitcnt lgkmcnt(0)
	s_barrier
	s_add_i32 s14, s13, 2
	s_cmpk_gt_u32 s13, 0x1fd
	s_cbranch_scc1 .LBB0_766
	s_mul_i32 s4, s14, 0xcccd
	s_lshr_b32 s4, s4, 18
	s_mul_i32 s4, s4, 5
	s_sub_i32 s4, s14, s4
	s_and_b32 s4, s4, 0xffff
	s_mulk_i32 s4, 0x2900
	s_add_i32 s4, s4, 0
	s_add_i32 s4, s4, 0x19c00
	v_mov_b32_e32 v0, s4
	v_lshl_add_u32 v28, v148, 1, s4
	v_add_u32_e32 v8, s4, v148
	v_add_u32_e32 v0, 0x2800, v0
	ds_read_u16_d16_hi v40, v28 offset:6656
	ds_read_u16_d16_hi v41, v28 offset:6784
	ds_read_u16_d16_hi v42, v28 offset:6912
	ds_read_u16_d16_hi v43, v28 offset:7040
	ds_read_u16_d16_hi v44, v28 offset:7168
	ds_read_u16_d16_hi v45, v28 offset:7296
	ds_read_u16_d16_hi v46, v28 offset:7424
	ds_read_u16_d16_hi v47, v28 offset:7552
	ds_read2_b32 v[2:3], v0 offset0:16 offset1:20
	ds_read2_b32 v[10:11], v0 offset0:24 offset1:28
	ds_read_u16_d16_hi v48, v28 offset:7680
	ds_read_u16_d16_hi v49, v28 offset:7808
	ds_read_u16_d16_hi v50, v28 offset:7936
	ds_read_u16 v51, v28 offset:8064
	ds_read_u8 v1, v8 offset:8512
	ds_read_u8 v9, v8 offset:8640
	ds_read_u8 v0, v8 offset:8576
	ds_read_u8 v8, v8 offset:8448
	ds_read_u16_d16_hi v58, v28 offset:512
	ds_read_u16_d16_hi v12, v28 offset:2560
	ds_read_u16_d16_hi v61, v28 offset:640
	ds_read_u16_d16_hi v13, v28 offset:2688
	ds_read_u16_d16_hi v64, v28 offset:768
	ds_read_u16_d16_hi v14, v28 offset:2816
	ds_read_u16_d16_hi v15, v28 offset:2944
	ds_read_u16_d16_hi v67, v28 offset:896
	ds_read_u16_d16_hi v68, v28 offset:6144
	ds_read_u16_d16_hi v69, v28 offset:6272
	ds_read_u16_d16_hi v70, v28 offset:6400
	ds_read_u16_d16_hi v71, v28 offset:6528
	ds_read_u16 v72, v28 offset:4608
	ds_read_u16 v74, v28 offset:4736
	ds_read_u16 v76, v28 offset:4864
	ds_read_u16 v78, v28 offset:4992
.LBB0_766:
	s_and_b64 vcc, exec, s[8:9]
	s_cbranch_vccnz .LBB0_757
	v_add_f32_e32 v28, 0, v80
	v_add_f32_e32 v28, v28, v81
	v_add_f32_e32 v28, v28, v82
	v_add_f32_e32 v28, v28, v83
	v_add_f32_e32 v29, v28, v56
	v_exp_f32_e32 v39, v28
	v_exp_f32_e32 v101, v29
	v_cvt_f32_u32_e32 v35, v21
	v_cvt_f32_u32_e32 v34, v20
	v_add_f32_e32 v38, v29, v57
	v_pk_mul_f32 v[36:37], v[4:5], v[24:25]
	v_cvt_f32_u32_e32 v117, v23
	v_cvt_f32_u32_e32 v116, v22
	v_add_f32_e32 v109, v38, v59
	v_pk_mul_f32 v[36:37], v[16:17], v[36:37]
	v_exp_f32_e32 v111, v38
	v_add_f32_e32 v92, v109, v60
	v_mul_f32_e32 v95, v36, v39
	v_mul_f32_e32 v93, v101, v84
	v_pk_mul_f32 v[30:31], v[34:35], s[12:13] op_sel_hi:[1,0]
	v_pk_mul_f32 v[112:113], v[4:5], v[26:27]
	v_rcp_f32_e32 v28, v101
	v_pk_mul_f32 v[30:31], v[30:31], v[36:37]
	v_mul_f32_e32 v101, v37, v101
	v_pk_mul_f32 v[36:37], v[116:117], s[12:13] op_sel_hi:[1,0]
	v_pk_mul_f32 v[118:119], v[18:19], v[112:113]
	v_rcp_f32_e32 v29, v111
	v_mul_f32_e32 v102, v111, v85
	v_exp_f32_e32 v120, v109
	v_mul_f32_e32 v111, v118, v111
	v_pk_mul_f32 v[36:37], v[36:37], v[118:119]
	v_exp_f32_e32 v118, v92
	v_pk_fma_f32 v[34:35], v[34:35], s[12:13], -1.0 op_sel_hi:[1,0,0]
	v_pk_fma_f32 v[116:117], v[116:117], s[12:13], -1.0 op_sel_hi:[1,0,0]
	v_pk_fma_f32 v[34:35], v[6:7], v[34:35], 1.0 op_sel_hi:[1,1,0]
	v_pk_fma_f32 v[116:117], v[6:7], v[116:117], 1.0 op_sel_hi:[1,1,0]
	v_pk_mul_f32 v[32:33], v[34:35], v[24:25]
	v_rcp_f32_e32 v34, v120
	v_mul_f32_e32 v109, v120, v86
	v_rcp_f32_e32 v35, v118
	s_and_b32 s4, s16, 3
	v_pk_mul_f32 v[38:39], v[116:117], v[26:27]
	s_mulk_i32 s4, 0x5f00
	v_mul_f32_e32 v97, v30, v28
	v_mul_f32_e32 v99, v32, v28
	v_mul_f32_e32 v103, v31, v29
	v_mul_f32_e32 v105, v33, v29
	v_mul_f32_e32 v113, v36, v34
	v_mul_f32_e32 v115, v38, v34
	v_mul_f32_e32 v117, v119, v120
	v_mul_f32_e32 v118, v118, v87
	v_mul_f32_e32 v119, v37, v35
	v_mul_f32_e32 v121, v39, v35
	s_add_i32 s8, s4, 0
	v_mov_b32_dpp v94, v93 quad_perm:[1,1,3,3] row_mask:0xf bank_mask:0xf bound_ctrl:1
	v_mov_b32_dpp v96, v95 quad_perm:[1,1,3,3] row_mask:0xf bank_mask:0xf bound_ctrl:1
	v_mov_b32_dpp v98, v97 quad_perm:[1,1,3,3] row_mask:0xf bank_mask:0xf bound_ctrl:1
	v_mov_b32_dpp v100, v99 quad_perm:[1,1,3,3] row_mask:0xf bank_mask:0xf bound_ctrl:1
	v_mov_b32_dpp v104, v101 quad_perm:[1,1,3,3] row_mask:0xf bank_mask:0xf bound_ctrl:1
	v_mov_b32_dpp v106, v102 quad_perm:[1,1,3,3] row_mask:0xf bank_mask:0xf bound_ctrl:1
	v_mov_b32_dpp v107, v103 quad_perm:[1,1,3,3] row_mask:0xf bank_mask:0xf bound_ctrl:1
	v_mov_b32_dpp v108, v105 quad_perm:[1,1,3,3] row_mask:0xf bank_mask:0xf bound_ctrl:1
	v_mov_b32_dpp v110, v109 quad_perm:[1,1,3,3] row_mask:0xf bank_mask:0xf bound_ctrl:1
	v_mov_b32_dpp v112, v111 quad_perm:[1,1,3,3] row_mask:0xf bank_mask:0xf bound_ctrl:1
	v_mov_b32_dpp v114, v113 quad_perm:[1,1,3,3] row_mask:0xf bank_mask:0xf bound_ctrl:1
	v_mov_b32_dpp v116, v115 quad_perm:[1,1,3,3] row_mask:0xf bank_mask:0xf bound_ctrl:1
	v_mov_b32_dpp v120, v117 quad_perm:[1,1,3,3] row_mask:0xf bank_mask:0xf bound_ctrl:1
	v_mov_b32_dpp v122, v118 quad_perm:[1,1,3,3] row_mask:0xf bank_mask:0xf bound_ctrl:1
	v_mov_b32_dpp v123, v119 quad_perm:[1,1,3,3] row_mask:0xf bank_mask:0xf bound_ctrl:1
	v_mov_b32_dpp v124, v121 quad_perm:[1,1,3,3] row_mask:0xf bank_mask:0xf bound_ctrl:1
	s_and_saveexec_b64 s[4:5], s[6:7]
	s_cbranch_execz .LBB0_756
	v_cvt_pk_bf16_f32 v101, v101, v104
	v_cvt_pk_bf16_f32 v93, v93, v94
	v_cvt_pk_bf16_f32 v94, v95, v96
	v_lshl_add_u32 v95, v52, 1, s8
	v_cvt_pk_bf16_f32 v102, v102, v106
	ds_write2_b32 v95, v94, v101 offset0:144 offset1:180
	v_add_u32_e32 v94, 0x800, v95
	v_cvt_pk_bf16_f32 v105, v105, v108
	v_cvt_pk_bf16_f32 v103, v103, v107
	v_cvt_pk_bf16_f32 v99, v99, v100
	v_cvt_pk_bf16_f32 v97, v97, v98
	ds_write2_b32 v94, v93, v102 offset0:208 offset1:244
	v_add_u32_e32 v93, 0x1400, v95
	v_add_u32_e32 v94, 0x1c00, v95
	v_cvt_pk_bf16_f32 v118, v118, v122
	v_cvt_pk_bf16_f32 v117, v117, v120
	v_cvt_pk_bf16_f32 v109, v109, v110
	v_cvt_pk_bf16_f32 v110, v111, v112
	ds_write2_b32 v93, v97, v103 offset0:16 offset1:52
	ds_write2_b32 v94, v99, v105 offset0:80 offset1:116
	ds_write2_b32 v95, v110, v117 offset0:216 offset1:252
	v_add_u32_e32 v95, 0xc00, v95
	v_cvt_pk_bf16_f32 v121, v121, v124
	v_cvt_pk_bf16_f32 v119, v119, v123
	v_cvt_pk_bf16_f32 v115, v115, v116
	v_cvt_pk_bf16_f32 v113, v113, v114
	ds_write2_b32 v95, v109, v118 offset0:24 offset1:60
	ds_write2_b32 v93, v113, v119 offset0:88 offset1:124
	ds_write2_b32 v94, v115, v121 offset0:152 offset1:188
	s_branch .LBB0_756

.LBB0_770:
	s_and_b64 vcc, exec, s[4:5]
	s_cbranch_vccz .LBB0_812
	s_cmp_gt_i32 s70, 2
	s_mov_b64 s[4:5], -1
	s_cbranch_scc0 .LBB0_810
	s_cmp_gt_i32 s70, 3
	v_and_b32_e32 v42, 3, v128
	s_cbranch_scc0 .LBB0_788
	s_add_i32 s4, 0, 0x19c00
	v_lshl_add_u32 v2, v148, 1, s4
	v_mov_b32_e32 v12, 0
	v_mov_b32_e32 v13, 0
	v_mov_b32_e32 v14, 0
	v_mov_b32_e32 v15, 0
	v_mov_b32_e32 v24, 0
	v_mov_b32_e32 v25, 0
	v_mov_b32_e32 v26, 0
	v_mov_b32_e32 v27, 0
	v_mov_b32_e32 v43, 0
	v_mov_b32_e32 v44, 0
	v_mov_b32_e32 v45, 0
	v_mov_b32_e32 v46, 0
	v_mov_b32_e32 v47, 0
	v_mov_b32_e32 v48, 0
	v_mov_b32_e32 v49, 0
	v_mov_b32_e32 v50, 0
	v_mov_b32_e32 v51, 0
	v_mov_b32_e32 v52, 0
	v_mov_b32_e32 v53, 0
	v_mov_b32_e32 v62, 0
	v_mov_b32_e32 v63, 0
	v_mov_b32_e32 v64, 0
	v_mov_b32_e32 v65, 0
	v_mov_b32_e32 v66, 0
	v_mov_b32_e32 v67, 0
	v_mov_b32_e32 v68, 0
	v_mov_b32_e32 v69, 0
	v_mov_b32_e32 v70, 0
	v_mov_b32_e32 v71, 0
	v_mov_b32_e32 v72, 0
	v_mov_b32_e32 v73, 0
	v_mov_b32_e32 v74, 0
	v_mov_b32_e32 v75, 0
	v_mov_b32_e32 v76, 0
	v_mov_b32_e32 v77, 0
	v_mov_b32_e32 v81, 0
	v_mov_b32_e32 v83, 0
	v_mov_b32_e32 v84, 0
	v_mov_b32_e32 v86, 0
	v_mov_b32_e32 v87, 0
	v_mov_b32_e32 v88, 0
	v_mov_b32_e32 v89, 0
	v_mov_b32_e32 v90, 0
	v_mov_b32_e32 v91, 0
	v_mov_b32_e32 v92, 0
	v_mov_b32_e32 v93, 0
	ds_read_u16_d16_hi v43, v2 offset:6656
	ds_read_u16_d16_hi v44, v2 offset:6784
	ds_read_u16_d16_hi v45, v2 offset:6912
	ds_read_u16_d16_hi v46, v2 offset:7040
	ds_read_u16_d16_hi v47, v2 offset:7168
	ds_read_u16_d16_hi v48, v2 offset:7296
	ds_read_u16_d16_hi v49, v2 offset:7424
	ds_read_u16_d16_hi v50, v2 offset:7552
	v_add_u32_e32 v3, s4, v148
	ds_read_u16_d16_hi v51, v2 offset:7680
	ds_read_u16_d16_hi v52, v2 offset:7808
	ds_read_u16_d16_hi v53, v2 offset:7936
	ds_read_u16 v54, v2 offset:8064
	ds_read_u8 v1, v3 offset:8256
	ds_read_u8 v9, v3 offset:8384
	ds_read_u8 v0, v3 offset:8320
	ds_read_u8 v8, v3 offset:8192
	ds_read_u16_d16_hi v63, v2
	ds_read_u16_d16_hi v12, v2 offset:2048
	ds_read_u16_d16_hi v66, v2 offset:128
	ds_read_u16_d16_hi v13, v2 offset:2176
	ds_read_u16_d16_hi v69, v2 offset:256
	ds_read_u16_d16_hi v14, v2 offset:2304
	ds_read_u16_d16_hi v15, v2 offset:2432
	ds_read_u16_d16_hi v73, v2 offset:384
	ds_read_u16_d16_hi v74, v2 offset:6144
	ds_read_u16_d16_hi v75, v2 offset:6272
	ds_read_u16_d16_hi v76, v2 offset:6400
	ds_read_u16_d16_hi v77, v2 offset:6528
	ds_read_u16 v78, v2 offset:4096
	ds_read_u16 v79, v2 offset:4224
	ds_read_u16 v80, v2 offset:4352
	ds_read_u16 v82, v2 offset:4480
	s_add_i32 s4, 0, 0x1c400
	v_mov_b32_e32 v5, s4
	s_add_i32 s4, 0, 0x1c410
	v_mov_b32_e32 v3, s4
	s_add_i32 s4, 0, 0x1c420
	v_mov_b32_e32 v7, s4
	s_add_i32 s4, 0, 0x1c430
	v_mov_b32_e32 v11, s4
	ds_read_b32 v2, v5
	ds_read_b32 v3, v3
	ds_read_b32 v10, v7
	ds_read_b32 v11, v11
	v_and_b32_e32 v16, 1, v128
	v_bfe_u32 v5, v128, 2, 1
	v_lshrrev_b32_e32 v7, 1, v148
	v_cmp_eq_u32_e64 s[6:7], 0, v16
	v_and_b32_e32 v16, 48, v128
	v_and_or_b32 v55, v7, 12, v42
	v_lshl_or_b32 v16, v5, 3, v16
	v_and_or_b32 v56, v55, 6, v16
	v_and_b32_e32 v16, 31, v128
	v_and_b32_e32 v17, 32, v128
	s_mov_b32 s11, 0
	v_mul_u32_u24_e32 v57, 0x50, v148
	v_mul_u32_u24_e32 v58, 48, v17
	v_mul_u32_u24_e32 v59, 48, v16
	v_and_b32_e32 v60, 16, v7
	v_lshlrev_b32_e32 v61, 7, v5
	v_mov_b32_e32 v5, v4
	v_mov_b32_e32 v7, v6
	s_mov_b32 s10, 0x3b808081
	s_waitcnt lgkmcnt(0)
	s_branch .LBB0_776
.LBB0_774:
	s_or_b64 exec, exec, s[4:5]
	v_add_f32_e32 v38, v98, v62
	v_add_f32_e32 v38, v38, v64
	v_add_f32_e32 v38, v38, v65
	v_add_f32_e32 v38, v38, v67
	v_add_f32_e32 v38, v38, v68
	v_add_f32_e32 v38, v38, v70
	v_add_f32_e32 v38, v38, v71
	v_add_f32_e32 v38, v38, v72
	v_add_f32_e32 v38, v38, v81
	v_add_f32_e32 v38, v38, v83
	v_add_f32_e32 v38, v38, v84
	v_lshlrev_b32_e32 v39, 16, v85
	v_add_f32_e32 v38, v38, v39
	v_exp_f32_e32 v38, v38
	s_nop 0
	v_pk_mul_f32 v[34:35], v[34:35], v[38:39] op_sel_hi:[1,0]
	v_pk_mul_f32 v[28:29], v[28:29], v[38:39] op_sel_hi:[1,0]
	v_pk_mul_f32 v[40:41], v[40:41], v[34:35]
	v_pk_mul_f32 v[34:35], v[34:35], v[36:37] neg_lo:[0,1] neg_hi:[0,1]
	v_pk_mul_f32 v[32:33], v[32:33], v[28:29]
	v_pk_mul_f32 v[28:29], v[28:29], v[30:31] neg_lo:[0,1] neg_hi:[0,1]
	v_add_u32_e32 v36, s8, v57
	v_cvt_pk_bf16_f32 v28, v28, v29
	v_cvt_pk_bf16_f32 v29, v34, v35
	v_cvt_pk_bf16_f32 v30, v32, v33
	v_cvt_pk_bf16_f32 v31, v40, v41
	v_add_u32_e32 v32, 0x2000, v36
	ds_write2_b64 v32, v[28:29], v[30:31] offset0:128 offset1:132
	v_lshl_or_b32 v28, v95, 16, v94
	v_lshl_or_b32 v29, v97, 16, v96
	v_add3_u32 v30, s8, v58, v59
	ds_write_b64 v30, v[28:29] offset:14336
	v_add_u32_e32 v28, s8, v61
	v_lshlrev_b32_e32 v29, 2, v60
	v_lshlrev_b32_e32 v30, 2, v55
	v_add3_u32 v28, v28, v29, v30
	ds_write_b32 v28, v38 offset:24064

.LBB0_776:
	s_add_i32 s14, s11, 1
	s_cmpk_lt_u32 s11, 0x200
	s_cselect_b64 s[12:13], -1, 0
	s_cmpk_gt_u32 s11, 0x1ff
	s_cbranch_scc1 .LBB0_778
	s_mul_i32 s4, s14, 0xcccd
	s_lshr_b32 s4, s4, 18
	s_mul_i32 s4, s4, 5
	s_sub_i32 s4, s14, s4
	s_and_b32 s4, s4, 0xffff
	s_mulk_i32 s4, 0x2900
	s_add_i32 s4, s4, 0
	s_add_i32 s4, s4, 0x19c00
	v_mov_b32_e32 v16, s4
	v_lshl_add_u32 v28, v148, 1, s4
	v_add_u32_e32 v20, s4, v148
	v_add_u32_e32 v18, 0x2800, v16
	ds_read_u16_d16_hi v62, v28 offset:6656
	ds_read_u16_d16_hi v64, v28 offset:6784
	ds_read_u16_d16_hi v65, v28 offset:6912
	ds_read_u16_d16_hi v67, v28 offset:7040
	ds_read_u16_d16_hi v68, v28 offset:7168
	ds_read_u16_d16_hi v70, v28 offset:7296
	ds_read_u16_d16_hi v71, v28 offset:7424
	ds_read_u16_d16_hi v72, v28 offset:7552
	ds_read2_b32 v[16:17], v18 offset1:4
	ds_read2_b32 v[18:19], v18 offset0:8 offset1:12
	ds_read_u16_d16_hi v81, v28 offset:7680
	ds_read_u16_d16_hi v83, v28 offset:7808
	ds_read_u16_d16_hi v84, v28 offset:7936
	ds_read_u16 v85, v28 offset:8064
	ds_read_u8 v21, v20 offset:8256
	ds_read_u8 v23, v20 offset:8384
	ds_read_u8 v22, v20 offset:8320
	ds_read_u8 v20, v20 offset:8192
	ds_read_u16_d16_hi v90, v28
	ds_read_u16_d16_hi v24, v28 offset:2048
	ds_read_u16_d16_hi v91, v28 offset:128
	ds_read_u16_d16_hi v25, v28 offset:2176
	ds_read_u16_d16_hi v92, v28 offset:256
	ds_read_u16_d16_hi v26, v28 offset:2304
	ds_read_u16_d16_hi v27, v28 offset:2432
	ds_read_u16_d16_hi v93, v28 offset:384
	ds_read_u16_d16_hi v86, v28 offset:6144
	ds_read_u16_d16_hi v87, v28 offset:6272
	ds_read_u16_d16_hi v88, v28 offset:6400
	ds_read_u16_d16_hi v89, v28 offset:6528
	ds_read_u16 v94, v28 offset:4096
	ds_read_u16 v95, v28 offset:4224
	ds_read_u16 v96, v28 offset:4352
	ds_read_u16 v97, v28 offset:4480
.LBB0_778:
	v_cndmask_b32_e64 v28, 0, 1, s[12:13]
	v_cmp_ne_u32_e64 s[8:9], 1, v28
	s_andn2_b64 vcc, exec, s[12:13]
	s_cbranch_vccnz .LBB0_782
	v_add_f32_e32 v28, 0, v74
	v_exp_f32_e32 v41, v28
	v_cvt_f32_u32_e32 v35, v1
	v_cvt_f32_u32_e32 v34, v8
	v_add_f32_e32 v29, v28, v75
	v_add_f32_e32 v40, v29, v76
	v_add_f32_e32 v98, v40, v77
	v_pk_mul_f32 v[36:37], v[4:5], v[12:13]
	v_cvt_f32_u32_e32 v121, v9
	v_cvt_f32_u32_e32 v120, v0
	v_mul_f32_e32 v99, v41, v63
	v_pk_mul_f32 v[30:31], v[34:35], s[10:11] op_sel_hi:[1,0]
	v_pk_mul_f32 v[38:39], v[36:37], v[2:3]
	v_exp_f32_e32 v115, v29
	v_rcp_f32_e32 v28, v41
	v_pk_mul_f32 v[30:31], v[30:31], v[38:39]
	v_mul_f32_e32 v39, v41, v39
	v_exp_f32_e32 v124, v40
	v_pk_mul_f32 v[116:117], v[4:5], v[14:15]
	v_pk_mul_f32 v[36:37], v[120:121], s[10:11] op_sel_hi:[1,0]
	v_pk_mul_f32 v[122:123], v[116:117], v[10:11]
	v_rcp_f32_e32 v29, v115
	v_mul_f32_e32 v106, v115, v66
	v_mul_f32_e32 v115, v115, v122
	v_pk_mul_f32 v[36:37], v[36:37], v[122:123]
	v_exp_f32_e32 v122, v98
	v_pk_fma_f32 v[34:35], v[34:35], s[10:11], -1.0 op_sel_hi:[1,0,0]
	v_pk_fma_f32 v[120:121], v[120:121], s[10:11], -1.0 op_sel_hi:[1,0,0]
	v_pk_fma_f32 v[34:35], v[6:7], v[34:35], 1.0 op_sel_hi:[1,1,0]
	v_pk_fma_f32 v[120:121], v[6:7], v[120:121], 1.0 op_sel_hi:[1,1,0]
	v_pk_mul_f32 v[32:33], v[34:35], v[12:13]
	v_rcp_f32_e32 v34, v124
	v_mul_f32_e32 v113, v124, v69
	v_rcp_f32_e32 v35, v122
	s_and_b32 s4, s11, 2
	v_pk_mul_f32 v[40:41], v[120:121], v[14:15]
	s_mulk_i32 s4, 0x5f00
	v_mul_f32_e32 v102, v28, v30
	v_mul_f32_e32 v104, v28, v32
	v_mul_f32_e32 v107, v29, v31
	v_mul_f32_e32 v109, v29, v33
	v_mul_f32_e32 v117, v34, v36
	v_mul_f32_e32 v119, v34, v40
	v_mul_f32_e32 v121, v124, v123
	v_mul_f32_e32 v122, v122, v73
	v_mul_f32_e32 v123, v35, v37
	v_mul_f32_e32 v125, v35, v41
	s_add_i32 s12, s4, 0
	v_mov_b32_dpp v100, v99 quad_perm:[1,1,3,3] row_mask:0xf bank_mask:0xf bound_ctrl:1
	v_mov_b32_dpp v101, v38 quad_perm:[1,1,3,3] row_mask:0xf bank_mask:0xf bound_ctrl:1
	v_mov_b32_dpp v103, v102 quad_perm:[1,1,3,3] row_mask:0xf bank_mask:0xf bound_ctrl:1
	v_mov_b32_dpp v105, v104 quad_perm:[1,1,3,3] row_mask:0xf bank_mask:0xf bound_ctrl:1
	v_mov_b32_dpp v108, v39 quad_perm:[1,1,3,3] row_mask:0xf bank_mask:0xf bound_ctrl:1
	v_mov_b32_dpp v110, v106 quad_perm:[1,1,3,3] row_mask:0xf bank_mask:0xf bound_ctrl:1
	v_mov_b32_dpp v111, v107 quad_perm:[1,1,3,3] row_mask:0xf bank_mask:0xf bound_ctrl:1
	v_mov_b32_dpp v112, v109 quad_perm:[1,1,3,3] row_mask:0xf bank_mask:0xf bound_ctrl:1
	v_mov_b32_dpp v114, v113 quad_perm:[1,1,3,3] row_mask:0xf bank_mask:0xf bound_ctrl:1
	v_mov_b32_dpp v116, v115 quad_perm:[1,1,3,3] row_mask:0xf bank_mask:0xf bound_ctrl:1
	v_mov_b32_dpp v118, v117 quad_perm:[1,1,3,3] row_mask:0xf bank_mask:0xf bound_ctrl:1
	v_mov_b32_dpp v120, v119 quad_perm:[1,1,3,3] row_mask:0xf bank_mask:0xf bound_ctrl:1
	v_mov_b32_dpp v124, v121 quad_perm:[1,1,3,3] row_mask:0xf bank_mask:0xf bound_ctrl:1
	v_mov_b32_dpp v126, v122 quad_perm:[1,1,3,3] row_mask:0xf bank_mask:0xf bound_ctrl:1
	v_mov_b32_dpp v127, v123 quad_perm:[1,1,3,3] row_mask:0xf bank_mask:0xf bound_ctrl:1
	v_mov_b32_dpp v129, v125 quad_perm:[1,1,3,3] row_mask:0xf bank_mask:0xf bound_ctrl:1
	s_and_saveexec_b64 s[4:5], s[6:7]
	s_cbranch_execz .LBB0_781
	v_cvt_pk_bf16_f32 v39, v39, v108
	v_cvt_pk_bf16_f32 v99, v99, v100
	v_cvt_pk_bf16_f32 v38, v38, v101
	v_lshl_add_u32 v100, v56, 1, s12
	v_cvt_pk_bf16_f32 v106, v106, v110
	ds_write2_b32 v100, v38, v39 offset1:36
	v_add_u32_e32 v38, 0x800, v100
	v_cvt_pk_bf16_f32 v109, v109, v112
	v_cvt_pk_bf16_f32 v107, v107, v111
	v_cvt_pk_bf16_f32 v104, v104, v105
	v_cvt_pk_bf16_f32 v102, v102, v103
	ds_write2_b32 v38, v99, v106 offset0:64 offset1:100
	v_add_u32_e32 v39, 0x1000, v100
	v_add_u32_e32 v99, 0x1800, v100
	v_cvt_pk_bf16_f32 v125, v125, v129
	v_cvt_pk_bf16_f32 v123, v123, v127
	v_cvt_pk_bf16_f32 v122, v122, v126
	v_cvt_pk_bf16_f32 v121, v121, v124
	v_cvt_pk_bf16_f32 v119, v119, v120
	v_cvt_pk_bf16_f32 v117, v117, v118
	v_cvt_pk_bf16_f32 v113, v113, v114
	v_cvt_pk_bf16_f32 v114, v115, v116
	ds_write2_b32 v39, v102, v107 offset0:128 offset1:164
	ds_write2_b32 v99, v104, v109 offset0:192 offset1:228
	ds_write2_b32 v100, v114, v121 offset0:72 offset1:108
	ds_write2_b32 v38, v113, v122 offset0:136 offset1:172
	ds_write2_b32 v39, v117, v123 offset0:200 offset1:236
	v_add_u32_e32 v38, 0x1c00, v100
	ds_write2_b32 v38, v119, v125 offset0:8 offset1:44
.LBB0_781:
	s_or_b64 exec, exec, s[4:5]
	v_add_f32_e32 v38, v98, v43
	v_add_f32_e32 v38, v38, v44
	v_add_f32_e32 v38, v38, v45
	v_add_f32_e32 v38, v38, v46
	v_add_f32_e32 v38, v38, v47
	v_add_f32_e32 v38, v38, v48
	v_add_f32_e32 v38, v38, v49
	v_add_f32_e32 v38, v38, v50
	v_add_f32_e32 v38, v38, v51
	v_add_f32_e32 v38, v38, v52
	v_add_f32_e32 v38, v38, v53
	v_lshlrev_b32_e32 v39, 16, v54
	v_add_f32_e32 v38, v38, v39
	v_exp_f32_e32 v38, v38
	s_nop 0
	v_pk_mul_f32 v[34:35], v[34:35], v[38:39] op_sel_hi:[1,0]
	v_pk_mul_f32 v[28:29], v[28:29], v[38:39] op_sel_hi:[1,0]
	v_pk_mul_f32 v[40:41], v[34:35], v[40:41]
	v_pk_mul_f32 v[34:35], v[34:35], v[36:37] neg_lo:[0,1] neg_hi:[0,1]
	v_pk_mul_f32 v[32:33], v[28:29], v[32:33]
	v_pk_mul_f32 v[28:29], v[28:29], v[30:31] neg_lo:[0,1] neg_hi:[0,1]
	v_add_u32_e32 v36, s12, v57
	v_cvt_pk_bf16_f32 v28, v28, v29
	v_cvt_pk_bf16_f32 v29, v34, v35
	v_cvt_pk_bf16_f32 v30, v32, v33
	v_cvt_pk_bf16_f32 v31, v40, v41
	v_add_u32_e32 v32, 0x2000, v36
	ds_write2_b64 v32, v[28:29], v[30:31] offset0:128 offset1:132
	v_lshl_or_b32 v28, v79, 16, v78
	v_lshl_or_b32 v29, v82, 16, v80
	v_add3_u32 v30, s12, v58, v59
	ds_write_b64 v30, v[28:29] offset:14336
	v_add_u32_e32 v28, s12, v61
	v_lshlrev_b32_e32 v29, 2, v60
	v_lshlrev_b32_e32 v30, 2, v55
	v_add3_u32 v28, v28, v29, v30
	ds_write_b32 v28, v38 offset:24064
.LBB0_782:
	s_waitcnt lgkmcnt(0)
	s_barrier
	s_add_i32 s12, s11, 2
	s_cmpk_gt_u32 s11, 0x1fd
	s_cbranch_scc1 .LBB0_784
	s_mul_i32 s4, s12, 0xcccd
	s_lshr_b32 s4, s4, 18
	s_mul_i32 s4, s4, 5
	s_sub_i32 s4, s12, s4
	s_and_b32 s4, s4, 0xffff
	s_mulk_i32 s4, 0x2900
	s_add_i32 s4, s4, 0
	s_add_i32 s4, s4, 0x19c00
	v_mov_b32_e32 v0, s4
	v_lshl_add_u32 v28, v148, 1, s4
	v_add_u32_e32 v8, s4, v148
	v_add_u32_e32 v0, 0x2800, v0
	ds_read_u16_d16_hi v43, v28 offset:6656
	ds_read_u16_d16_hi v44, v28 offset:6784
	ds_read_u16_d16_hi v45, v28 offset:6912
	ds_read_u16_d16_hi v46, v28 offset:7040
	ds_read_u16_d16_hi v47, v28 offset:7168
	ds_read_u16_d16_hi v48, v28 offset:7296
	ds_read_u16_d16_hi v49, v28 offset:7424
	ds_read_u16_d16_hi v50, v28 offset:7552
	ds_read2_b32 v[2:3], v0 offset1:4
	ds_read2_b32 v[10:11], v0 offset0:8 offset1:12
	ds_read_u16_d16_hi v51, v28 offset:7680
	ds_read_u16_d16_hi v52, v28 offset:7808
	ds_read_u16_d16_hi v53, v28 offset:7936
	ds_read_u16 v54, v28 offset:8064
	ds_read_u8 v1, v8 offset:8256
	ds_read_u8 v9, v8 offset:8384
	ds_read_u8 v0, v8 offset:8320
	ds_read_u8 v8, v8 offset:8192
	ds_read_u16_d16_hi v63, v28
	ds_read_u16_d16_hi v12, v28 offset:2048
	ds_read_u16_d16_hi v66, v28 offset:128
	ds_read_u16_d16_hi v13, v28 offset:2176
	ds_read_u16_d16_hi v69, v28 offset:256
	ds_read_u16_d16_hi v14, v28 offset:2304
	ds_read_u16_d16_hi v15, v28 offset:2432
	ds_read_u16_d16_hi v73, v28 offset:384
	ds_read_u16_d16_hi v74, v28 offset:6144
	ds_read_u16_d16_hi v75, v28 offset:6272
	ds_read_u16_d16_hi v76, v28 offset:6400
	ds_read_u16_d16_hi v77, v28 offset:6528
	ds_read_u16 v78, v28 offset:4096
	ds_read_u16 v79, v28 offset:4224
	ds_read_u16 v80, v28 offset:4352
	ds_read_u16 v82, v28 offset:4480
.LBB0_784:
	s_and_b64 vcc, exec, s[8:9]
	s_cbranch_vccnz .LBB0_775
	v_add_f32_e32 v28, 0, v86
	v_exp_f32_e32 v41, v28
	v_cvt_f32_u32_e32 v35, v21
	v_cvt_f32_u32_e32 v34, v20
	v_add_f32_e32 v29, v28, v87
	v_add_f32_e32 v40, v29, v88
	v_add_f32_e32 v98, v40, v89
	v_pk_mul_f32 v[36:37], v[4:5], v[24:25]
	v_cvt_f32_u32_e32 v121, v23
	v_cvt_f32_u32_e32 v120, v22
	v_mul_f32_e32 v99, v41, v90
	v_pk_mul_f32 v[30:31], v[34:35], s[10:11] op_sel_hi:[1,0]
	v_pk_mul_f32 v[38:39], v[16:17], v[36:37]
	v_exp_f32_e32 v115, v29
	v_rcp_f32_e32 v28, v41
	v_pk_mul_f32 v[30:31], v[30:31], v[38:39]
	v_mul_f32_e32 v39, v39, v41
	v_exp_f32_e32 v124, v40
	v_pk_mul_f32 v[116:117], v[4:5], v[26:27]
	v_pk_mul_f32 v[36:37], v[120:121], s[10:11] op_sel_hi:[1,0]
	v_pk_mul_f32 v[122:123], v[18:19], v[116:117]
	v_rcp_f32_e32 v29, v115
	v_mul_f32_e32 v106, v115, v91
	v_mul_f32_e32 v115, v122, v115
	v_pk_mul_f32 v[36:37], v[36:37], v[122:123]
	v_exp_f32_e32 v122, v98
	v_pk_fma_f32 v[34:35], v[34:35], s[10:11], -1.0 op_sel_hi:[1,0,0]
	v_pk_fma_f32 v[120:121], v[120:121], s[10:11], -1.0 op_sel_hi:[1,0,0]
	v_pk_fma_f32 v[34:35], v[6:7], v[34:35], 1.0 op_sel_hi:[1,1,0]
	v_pk_fma_f32 v[120:121], v[6:7], v[120:121], 1.0 op_sel_hi:[1,1,0]
	v_pk_mul_f32 v[32:33], v[34:35], v[24:25]
	v_rcp_f32_e32 v34, v124
	v_mul_f32_e32 v113, v124, v92
	v_rcp_f32_e32 v35, v122
	s_and_b32 s4, s14, 3
	v_pk_mul_f32 v[40:41], v[120:121], v[26:27]
	s_mulk_i32 s4, 0x5f00
	v_mul_f32_e32 v102, v30, v28
	v_mul_f32_e32 v104, v32, v28
	v_mul_f32_e32 v107, v31, v29
	v_mul_f32_e32 v109, v33, v29
	v_mul_f32_e32 v117, v36, v34
	v_mul_f32_e32 v119, v40, v34
	v_mul_f32_e32 v121, v123, v124
	v_mul_f32_e32 v122, v122, v93
	v_mul_f32_e32 v123, v37, v35
	v_mul_f32_e32 v125, v41, v35
	s_add_i32 s8, s4, 0
	v_mov_b32_dpp v100, v99 quad_perm:[1,1,3,3] row_mask:0xf bank_mask:0xf bound_ctrl:1
	v_mov_b32_dpp v101, v38 quad_perm:[1,1,3,3] row_mask:0xf bank_mask:0xf bound_ctrl:1
	v_mov_b32_dpp v103, v102 quad_perm:[1,1,3,3] row_mask:0xf bank_mask:0xf bound_ctrl:1
	v_mov_b32_dpp v105, v104 quad_perm:[1,1,3,3] row_mask:0xf bank_mask:0xf bound_ctrl:1
	v_mov_b32_dpp v108, v39 quad_perm:[1,1,3,3] row_mask:0xf bank_mask:0xf bound_ctrl:1
	v_mov_b32_dpp v110, v106 quad_perm:[1,1,3,3] row_mask:0xf bank_mask:0xf bound_ctrl:1
	v_mov_b32_dpp v111, v107 quad_perm:[1,1,3,3] row_mask:0xf bank_mask:0xf bound_ctrl:1
	v_mov_b32_dpp v112, v109 quad_perm:[1,1,3,3] row_mask:0xf bank_mask:0xf bound_ctrl:1
	v_mov_b32_dpp v114, v113 quad_perm:[1,1,3,3] row_mask:0xf bank_mask:0xf bound_ctrl:1
	v_mov_b32_dpp v116, v115 quad_perm:[1,1,3,3] row_mask:0xf bank_mask:0xf bound_ctrl:1
	v_mov_b32_dpp v118, v117 quad_perm:[1,1,3,3] row_mask:0xf bank_mask:0xf bound_ctrl:1
	v_mov_b32_dpp v120, v119 quad_perm:[1,1,3,3] row_mask:0xf bank_mask:0xf bound_ctrl:1
	v_mov_b32_dpp v124, v121 quad_perm:[1,1,3,3] row_mask:0xf bank_mask:0xf bound_ctrl:1
	v_mov_b32_dpp v126, v122 quad_perm:[1,1,3,3] row_mask:0xf bank_mask:0xf bound_ctrl:1
	v_mov_b32_dpp v127, v123 quad_perm:[1,1,3,3] row_mask:0xf bank_mask:0xf bound_ctrl:1
	v_mov_b32_dpp v129, v125 quad_perm:[1,1,3,3] row_mask:0xf bank_mask:0xf bound_ctrl:1
	s_and_saveexec_b64 s[4:5], s[6:7]
	s_cbranch_execz .LBB0_774
	v_cvt_pk_bf16_f32 v39, v39, v108
	v_cvt_pk_bf16_f32 v99, v99, v100
	v_cvt_pk_bf16_f32 v38, v38, v101
	v_lshl_add_u32 v100, v56, 1, s8
	v_cvt_pk_bf16_f32 v106, v106, v110
	ds_write2_b32 v100, v38, v39 offset1:36
	v_add_u32_e32 v38, 0x800, v100
	v_cvt_pk_bf16_f32 v109, v109, v112
	v_cvt_pk_bf16_f32 v107, v107, v111
	v_cvt_pk_bf16_f32 v104, v104, v105
	v_cvt_pk_bf16_f32 v102, v102, v103
	ds_write2_b32 v38, v99, v106 offset0:64 offset1:100
	v_add_u32_e32 v39, 0x1000, v100
	v_add_u32_e32 v99, 0x1800, v100
	v_cvt_pk_bf16_f32 v125, v125, v129
	v_cvt_pk_bf16_f32 v123, v123, v127
	v_cvt_pk_bf16_f32 v122, v122, v126
	v_cvt_pk_bf16_f32 v121, v121, v124
	v_cvt_pk_bf16_f32 v119, v119, v120
	v_cvt_pk_bf16_f32 v117, v117, v118
	v_cvt_pk_bf16_f32 v113, v113, v114
	v_cvt_pk_bf16_f32 v114, v115, v116
	ds_write2_b32 v39, v102, v107 offset0:128 offset1:164
	ds_write2_b32 v99, v104, v109 offset0:192 offset1:228
	ds_write2_b32 v100, v114, v121 offset0:72 offset1:108
	ds_write2_b32 v38, v113, v122 offset0:136 offset1:172
	ds_write2_b32 v39, v117, v123 offset0:200 offset1:236
	v_add_u32_e32 v38, 0x1c00, v100
	ds_write2_b32 v38, v119, v125 offset0:8 offset1:44
	s_branch .LBB0_774
